# memory-attention items: K/V tiles loaded once in the prologue, redundant in-loop reloads removed
# baseline (speedup 1.0000x reference)
; DI int my_tid() { int t = threadIdx.x; asm volatile("" : "+v"(t)); return t; }
; #define KLOAD(kf_, base)                                                                       \
;   { _Pragma("unroll") for (int ks = 0; ks < NKS; ks++) kf_[ks] = *(const bf16x8*)((base) + kfo + ks * 32); }
; #define QKM(dst, kf_)                                                                          \
;   {                                                                                            \
;     _Pragma("unroll") for (int i = 0; i < 16; i++) dst[i] = 0.f;                               \
;     _Pragma("unroll") for (int ks = 0; ks < NKS; ks++) dst = MFMA(kf_[ks], qf[ks], dst);       \
;   }
; template <int DK>
; DI void attn_core(const bf16x8 (&qf)[DK / 16], const short* Kg, const short* VTg, size_t ldvt, int ntiles, char* smem,
;                   f32x16 (&O)[2], float& lsum) {
;     ...
;   for (int i = 0; i < NKC; i++) { int c = tid + 512 * i; koff[i] = (c / KCH) * KROW + (c % KCH) * 16; }
;   const int vrow = tid >> 4, vcol = tid & 15;
;   const short* vg = VTg + (size_t)vrow * ldvt + vcol * 8;
;   const int voff = KT_BYTES + vrow * VROW + vcol * 16;
; #pragma unroll
;   for (int i = 0; i < 16; i++) { O[0][i] = 0.f; O[1][i] = 0.f; }
;   float l0 = 0.f;
;     ...
;   const int kfo = pr * KROW + h * 16;
;   const int vfo = KT_BYTES + r * VROW + h * 16;
;   AGLOAD(0);
;   ASTORE(0);
;   AGLOAD(ntiles > 1 ? 1 : 0);
;   ASTORE(1);
;   __syncthreads();
;   f32x16 Sc;
;   {
;     bf16x8 kf[NKS];
;     KLOAD(kf, smem);
;     QKM(Sc, kf);
; DI void memattn_item(PRef p, int layer, int mt, int head, char* smem) {
;   const int tid = my_tid(), lane = tid & 63, w = tid >> 6, r = lane & 31, h = lane >> 5;
;   const int tok = mt * 256 + w * 32 + r;
;   const int seq = tok_seq(mt * 256);
;   const short* Q = (const short*)(p.ws + OFF_QMEM);
;   bf16x8 qf[4];
; #pragma unroll
;   for (int ks = 0; ks < 4; ks++) qf[ks] = *(const bf16x8*)(Q + (size_t)tok * 256 + head * 64 + ks * 16 + 8 * h);
;   const size_t hb = ((size_t)(layer * NSEQ + seq) * 4 + head) * 256 * 64;
.LBB0_142:
	s_cmpk_gt_i32 s39, 0x9ff
	s_mov_b64 s[42:43], -1
	s_cbranch_scc0 .LBB0_144
	s_waitcnt vmcnt(0)
	v_mov_b32_e32 v2, v196
	s_add_i32 s28, s38, 0x4000
	v_ashrrev_i32_e32 v0, 1, v2
	s_and_b32 s28, s28, 0x7fffff00
	v_and_b32_e32 v0, 0xffffffe0, v0
	v_add_u32_e32 v0, s28, v0
	v_and_or_b32 v80, v2, 31, v0
	v_ashrrev_i32_e32 v81, 31, v80
	s_and_b32 s42, s39, 3
	v_lshlrev_b64 v[0:1], 9, v[80:81]
	v_lshl_add_u64 v[0:1], s[6:7], 0, v[0:1]
	s_lshl_b32 s30, s42, 7
	v_lshrrev_b32_e32 v2, 1, v2
	v_lshl_add_u64 v[0:1], v[0:1], 0, s[30:31]
	s_waitcnt vmcnt(7)
	v_and_b32_e32 v128, 16, v2
	v_lshl_add_u64 v[0:1], v[0:1], 0, v[128:129]
	s_lshr_b32 s28, s38, 12
	v_mov_b32_e32 v2, v196
	s_add_i32 s16, s39, 0xfffff600
	global_load_dwordx4 v[60:63], v[0:1], off
	global_load_dwordx4 v[56:59], v[0:1], off offset:32
	global_load_dwordx4 v[52:55], v[0:1], off offset:64
	global_load_dwordx4 v[48:51], v[0:1], off offset:96
	s_add_i32 s28, s28, 1
	s_cmpk_gt_u32 s16, 0xff
	v_lshlrev_b32_e32 v0, 1, v2
	v_and_b32_e32 v10, 8, v0
	v_ashrrev_i32_e32 v0, 31, v2
	s_cselect_b32 s16, s28, 0
	v_readlane_b32 s28, v226, 46
	v_lshrrev_b32_e32 v0, 29, v0
	v_readlane_b32 s29, v226, 47
	s_mul_i32 s28, s28, 17
	v_add_u32_e32 v0, v2, v0
	s_add_i32 s28, s16, s28
	s_mov_b32 s29, s31
	v_lshrrev_b32_e32 v0, 3, v0
	s_lshl_b64 s[28:29], s[28:29], 17
	s_lshl_b32 s16, s42, 15
	v_add_lshl_u32 v81, v0, v2, 4
	v_add_u32_e32 v0, 0x200, v2
	s_or_b32 s16, s28, s16
	v_ashrrev_i32_e32 v1, 31, v0
	v_lshlrev_b32_e32 v4, 4, v2
	s_add_u32 s42, s10, s16
	v_lshrrev_b32_e32 v1, 29, v1
	v_and_b32_e32 v128, 0xf0, v4
	v_lshlrev_b32_e32 v4, 3, v2
	s_addc_u32 s43, s11, s29
	v_add_u32_e32 v1, v0, v1
	v_ashrrev_i32_e32 v16, 4, v2
	v_ashrrev_i32_e32 v5, 31, v4
	s_add_u32 s28, s12, s16
	v_lshrrev_b32_e32 v1, 3, v1
	v_ashrrev_i32_e32 v17, 31, v16
	v_lshlrev_b64 v[18:19], 1, v[4:5]
	v_add_u32_e32 v4, 0x1000, v4
	s_addc_u32 s29, s13, s29
	v_add_lshl_u32 v92, v1, v0, 4
	v_lshlrev_b64 v[0:1], 9, v[16:17]
	v_ashrrev_i32_e32 v5, 31, v4
	v_lshrrev_b32_e32 v3, 1, v2
	v_lshl_add_u64 v[8:9], s[28:29], 0, v[0:1]
	v_lshl_add_u64 v[0:1], s[42:43], 0, v[18:19]
	v_lshlrev_b64 v[20:21], 1, v[4:5]
	v_and_b32_e32 v32, 31, v2
	v_and_b32_e32 v11, 4, v3
	v_and_b32_e32 v12, 19, v2
	v_and_b32_e32 v33, 16, v3
	global_load_dwordx4 v[0:3], v[0:1], off
	v_lshl_add_u64 v[4:5], s[42:43], 0, v[20:21]
	v_lshl_add_u64 v[84:85], v[8:9], 0, v[128:129]
	global_load_dwordx4 v[4:7], v[4:5], off
	v_or3_b32 v10, v12, v10, v11
	s_movk_i32 s16, 0x90
	v_add_co_u32_e32 v86, vcc, s84, v84
	v_mad_u32_u24 v93, v10, s16, v33
	global_load_dwordx4 v[8:11], v[84:85], off
	v_addc_co_u32_e32 v87, vcc, 0, v85, vcc
	global_load_dwordx4 v[12:15], v[86:87], off
	s_movk_i32 s16, 0x110
	v_mad_u64_u32 v[82:83], s[28:29], v16, s16, v[128:129]
	s_add_u32 s28, s42, 0x4000
	s_addc_u32 s29, s43, 0
	v_lshl_add_u64 v[88:89], s[28:29], 0, v[18:19]
	v_lshl_add_u64 v[90:91], s[28:29], 0, v[20:21]
	v_add_u32_e32 v94, 0x11800, v82
	global_load_dwordx4 v[64:67], v[88:89], off
	global_load_dwordx4 v[68:71], v[90:91], off
	global_load_dwordx4 v[72:75], v[84:85], off offset:256
	global_load_dwordx4 v[76:79], v[86:87], off offset:256
	s_waitcnt vmcnt(7)
	ds_write_b128 v81, v[0:3]
	s_waitcnt vmcnt(6)
	ds_write_b128 v92, v[4:7]
	s_waitcnt vmcnt(5)
	ds_write_b128 v82, v[8:11] offset:18432
	s_waitcnt vmcnt(4)
	ds_write_b128 v82, v[12:15] offset:27136
	s_waitcnt vmcnt(3)
	ds_write_b128 v81, v[64:67] offset:35840
	s_waitcnt vmcnt(2)
	ds_write_b128 v92, v[68:71] offset:35840
	s_waitcnt vmcnt(1)
	ds_write_b128 v82, v[72:75] offset:54272
	s_waitcnt vmcnt(0)
	ds_write_b128 v82, v[76:79] offset:62976
	s_waitcnt lgkmcnt(0)
	s_barrier
	ds_read_b128 v[0:3], v93
	ds_read_b128 v[16:19], v93 offset:32
	ds_read_b128 v[20:23], v93 offset:64
	ds_read_b128 v[24:27], v93 offset:96
	s_waitcnt lgkmcnt(3)
	v_mfma_f32_32x32x16_bf16 v[0:15], v[0:3], v[60:63], 0
	s_waitcnt lgkmcnt(2)
	v_mfma_f32_32x32x16_bf16 v[0:15], v[16:19], v[56:59], v[0:15]
	s_waitcnt lgkmcnt(1)
	v_mfma_f32_32x32x16_bf16 v[0:15], v[20:23], v[52:55], v[0:15]
	s_waitcnt lgkmcnt(0)
	v_mfma_f32_32x32x16_bf16 v[0:15], v[24:27], v[48:51], v[0:15]
	ds_read_b128 v[16:19], v93 offset:4608
	ds_read_b128 v[20:23], v93 offset:4640
	ds_read_b128 v[24:27], v93 offset:4672
	ds_read_b128 v[28:31], v93 offset:4704
	s_nop 7
	v_exp_f32_e32 v0, v0
	v_exp_f32_e32 v1, v1
	v_exp_f32_e32 v2, v2
	v_exp_f32_e32 v3, v3
	v_add_f32_e32 v34, 0, v0
	v_exp_f32_e32 v4, v4
	v_add_f32_e32 v34, v1, v34
	v_exp_f32_e32 v5, v5
	v_add_f32_e32 v34, v2, v34
	v_exp_f32_e32 v6, v6
	v_add_f32_e32 v34, v3, v34
	v_exp_f32_e32 v7, v7
	v_add_f32_e32 v34, v4, v34
	v_exp_f32_e32 v8, v8
	v_add_f32_e32 v34, v5, v34
	v_exp_f32_e32 v9, v9
	v_add_f32_e32 v34, v6, v34
	v_exp_f32_e32 v10, v10
	v_add_f32_e32 v34, v7, v34
	v_exp_f32_e32 v11, v11
	v_add_f32_e32 v34, v8, v34
	v_exp_f32_e32 v12, v12
	v_add_f32_e32 v34, v9, v34
	v_exp_f32_e32 v13, v13
	v_add_f32_e32 v34, v10, v34
	v_exp_f32_e32 v14, v14
	v_add_f32_e32 v34, v11, v34
	v_exp_f32_e32 v15, v15
	v_add_f32_e32 v34, v12, v34
	v_add_f32_e32 v34, v13, v34
	v_add_f32_e32 v34, v14, v34
	v_add_f32_e32 v34, v15, v34
	v_cvt_pk_bf16_f32 v96, v0, v1
	v_cvt_pk_bf16_f32 v100, v8, v9
	v_cvt_pk_bf16_f32 v97, v2, v3
	v_cvt_pk_bf16_f32 v101, v10, v11
	v_cvt_pk_bf16_f32 v98, v4, v5
	v_cvt_pk_bf16_f32 v102, v12, v13
	v_cvt_pk_bf16_f32 v99, v6, v7
	v_cvt_pk_bf16_f32 v103, v14, v15
	s_waitcnt lgkmcnt(3)
	v_mfma_f32_32x32x16_bf16 v[0:15], v[16:19], v[60:63], 0
	s_waitcnt lgkmcnt(2)
	v_mfma_f32_32x32x16_bf16 v[0:15], v[20:23], v[56:59], v[0:15]
	s_waitcnt lgkmcnt(1)
	v_mfma_f32_32x32x16_bf16 v[0:15], v[24:27], v[52:55], v[0:15]
	s_waitcnt lgkmcnt(0)
; #define KLOAD(kf_, base)                                                                       \
;   { _Pragma("unroll") for (int ks = 0; ks < NKS; ks++) kf_[ks] = *(const bf16x8*)((base) + kfo + ks * 32); }
; #define VLOAD(vf_, base)                                                                       \
;   { _Pragma("unroll") for (int q = 0; q < 4; q++) vf_[q] = *(const bf16x8*)((base) + vfo + (q >> 1) * 32 * VROW + (q & 1) * 32); }
; #define QKM(dst, kf_)                                                                          \
;   {                                                                                            \
;     _Pragma("unroll") for (int i = 0; i < 16; i++) dst[i] = 0.f;                               \
;     _Pragma("unroll") for (int ks = 0; ks < NKS; ks++) dst = MFMA(kf_[ks], qf[ks], dst);       \
;   }
; #define SB() __builtin_amdgcn_sched_barrier(0)
; template <int DK>
; DI void attn_core(const bf16x8 (&qf)[DK / 16], const short* Kg, const short* VTg, size_t ldvt, int ntiles, char* smem,
;                   f32x16 (&O)[2], float& lsum) {
;     ...
;     KLOAD(kf, cur + 32 * KROW);
;     SB();
;     SOFTMAX(Sc, pa, pb, l0);
;     SB();
;     QKM(Sn, kf);
;     SB();
;     KLOAD(kf, cur + 64 * KROW);
;     VLOAD(vf, cur);
;     SB();
;     SOFTMAX(Sn, qa, qb, l0);
;     SB();
;     QKM(Sc, kf);
;     PVM(vf, pa, pb);
;     SB();
;     KLOAD(kf, cur + 96 * KROW);
;     VLOAD(vf, cur + 64);
;     SB();
;     SOFTMAX(Sc, pa, pb, l0);
;     SB();
;     QKM(Sn, kf);
;     PVM(vf, qa, qb);
;     SB();
;     KLOAD(kf, nxt);
;     VLOAD(vf, cur + 128);
;     SB();
;     SOFTMAX(Sn, qa, qb, l0);
;     SB();
;     QKM(Sc, kf);
;     PVM(vf, pa, pb);
;     SB();
;     VLOAD(vf, cur + 192);
;     PVM(vf, qa, qb);
;     ASTORE(sw);
;     __syncthreads();
	v_mfma_f32_32x32x16_bf16 v[0:15], v[28:31], v[48:51], v[0:15]
	v_mad_u32_u24 v83, v32, s16, v33
	ds_read_b128 v[16:19], v93 offset:9216
	ds_read_b128 v[20:23], v93 offset:9248
	ds_read_b128 v[24:27], v93 offset:9280
	ds_read_b128 v[28:31], v93 offset:9312
	ds_read_b128 v[104:107], v83 offset:18432
	ds_read_b128 v[108:111], v83 offset:18464
	ds_read_b128 v[112:115], v83 offset:27136
	ds_read_b128 v[116:119], v83 offset:27168
	s_nop 2
	v_exp_f32_e32 v0, v0
	v_exp_f32_e32 v1, v1
	v_exp_f32_e32 v2, v2
	v_exp_f32_e32 v3, v3
	v_add_f32_e32 v32, v0, v34
	v_exp_f32_e32 v4, v4
	v_add_f32_e32 v32, v1, v32
	v_exp_f32_e32 v5, v5
	v_add_f32_e32 v32, v2, v32
	v_exp_f32_e32 v6, v6
	v_add_f32_e32 v32, v3, v32
	v_exp_f32_e32 v7, v7
	v_add_f32_e32 v32, v4, v32
	v_exp_f32_e32 v8, v8
	v_add_f32_e32 v32, v5, v32
	v_exp_f32_e32 v9, v9
	v_add_f32_e32 v32, v6, v32
	v_exp_f32_e32 v10, v10
	v_add_f32_e32 v32, v7, v32
	v_exp_f32_e32 v11, v11
	v_add_f32_e32 v32, v8, v32
	v_exp_f32_e32 v12, v12
	v_add_f32_e32 v32, v9, v32
	v_exp_f32_e32 v13, v13
	v_add_f32_e32 v32, v10, v32
	v_exp_f32_e32 v14, v14
	v_add_f32_e32 v32, v11, v32
	v_exp_f32_e32 v15, v15
	v_add_f32_e32 v32, v12, v32
	v_add_f32_e32 v32, v13, v32
	v_add_f32_e32 v32, v14, v32
	v_add_f32_e32 v95, v15, v32
	v_cvt_pk_bf16_f32 v120, v0, v1
	v_cvt_pk_bf16_f32 v124, v8, v9
	v_cvt_pk_bf16_f32 v121, v2, v3
	v_cvt_pk_bf16_f32 v125, v10, v11
	v_cvt_pk_bf16_f32 v122, v4, v5
	v_cvt_pk_bf16_f32 v126, v12, v13
	v_cvt_pk_bf16_f32 v123, v6, v7
	v_cvt_pk_bf16_f32 v127, v14, v15
	s_waitcnt lgkmcnt(7)
	v_mfma_f32_32x32x16_bf16 v[32:47], v[16:19], v[60:63], 0
	s_waitcnt lgkmcnt(6)
	v_mfma_f32_32x32x16_bf16 v[32:47], v[20:23], v[56:59], v[32:47]
	s_waitcnt lgkmcnt(5)
	v_mfma_f32_32x32x16_bf16 v[32:47], v[24:27], v[52:55], v[32:47]
	s_waitcnt lgkmcnt(4)
	v_mfma_f32_32x32x16_bf16 v[32:47], v[28:31], v[48:51], v[32:47]
	s_waitcnt lgkmcnt(3)
	v_mfma_f32_32x32x16_bf16 v[16:31], v[104:107], v[96:99], 0
	s_waitcnt lgkmcnt(1)
	v_mfma_f32_32x32x16_bf16 v[0:15], v[112:115], v[96:99], 0
	v_mfma_f32_32x32x16_bf16 v[16:31], v[108:111], v[100:103], v[16:31]
	s_waitcnt lgkmcnt(0)
	v_mfma_f32_32x32x16_bf16 v[0:15], v[116:119], v[100:103], v[0:15]
	ds_read_b128 v[96:99], v93 offset:13824
	ds_read_b128 v[100:103], v93 offset:13856
	ds_read_b128 v[104:107], v93 offset:13888
	ds_read_b128 v[108:111], v93 offset:13920
	ds_read_b128 v[112:115], v83 offset:18496
	ds_read_b128 v[116:119], v83 offset:18528
	ds_read_b128 v[130:133], v83 offset:27200
	ds_read_b128 v[134:137], v83 offset:27232
	v_exp_f32_e32 v32, v32
	v_exp_f32_e32 v33, v33
	v_exp_f32_e32 v34, v34
	v_exp_f32_e32 v35, v35
	v_add_f32_e32 v95, v32, v95
	v_exp_f32_e32 v36, v36
	v_add_f32_e32 v95, v33, v95
	v_exp_f32_e32 v37, v37
	v_add_f32_e32 v95, v34, v95
	v_exp_f32_e32 v38, v38
	v_add_f32_e32 v95, v35, v95
	v_exp_f32_e32 v39, v39
	v_add_f32_e32 v95, v36, v95
	v_exp_f32_e32 v40, v40
	v_add_f32_e32 v95, v37, v95
	v_exp_f32_e32 v41, v41
	v_add_f32_e32 v95, v38, v95
	v_exp_f32_e32 v42, v42
	v_add_f32_e32 v95, v39, v95
	v_exp_f32_e32 v43, v43
	v_add_f32_e32 v95, v40, v95
	v_exp_f32_e32 v44, v44
	v_add_f32_e32 v95, v41, v95
	v_exp_f32_e32 v45, v45
	v_add_f32_e32 v95, v42, v95
	v_exp_f32_e32 v46, v46
	v_add_f32_e32 v95, v43, v95
	v_exp_f32_e32 v47, v47
	v_add_f32_e32 v95, v44, v95
	v_add_f32_e32 v95, v45, v95
	v_add_f32_e32 v95, v46, v95
	v_add_f32_e32 v95, v47, v95
	v_cvt_pk_bf16_f32 v138, v32, v33
	v_cvt_pk_bf16_f32 v142, v40, v41
	v_cvt_pk_bf16_f32 v139, v34, v35
	v_cvt_pk_bf16_f32 v143, v42, v43
	v_cvt_pk_bf16_f32 v140, v36, v37
	v_cvt_pk_bf16_f32 v144, v44, v45
	v_cvt_pk_bf16_f32 v141, v38, v39
	v_cvt_pk_bf16_f32 v145, v46, v47
	s_waitcnt lgkmcnt(3)
	v_mfma_f32_32x32x16_bf16 v[16:31], v[112:115], v[120:123], v[16:31]
	s_waitcnt lgkmcnt(1)
	v_mfma_f32_32x32x16_bf16 v[0:15], v[130:133], v[120:123], v[0:15]
	v_mfma_f32_32x32x16_bf16 v[16:31], v[116:119], v[124:127], v[16:31]
	s_waitcnt lgkmcnt(0)
	v_mfma_f32_32x32x16_bf16 v[0:15], v[134:137], v[124:127], v[0:15]
	v_mfma_f32_32x32x16_bf16 v[32:47], v[96:99], v[60:63], 0
	v_mfma_f32_32x32x16_bf16 v[32:47], v[100:103], v[56:59], v[32:47]
	v_mfma_f32_32x32x16_bf16 v[32:47], v[104:107], v[52:55], v[32:47]
	ds_read_b128 v[96:99], v93 offset:35840
	ds_read_b128 v[100:103], v93 offset:35872
	ds_read_b128 v[104:107], v93 offset:35904
	ds_read_b128 v[112:115], v93 offset:35936
	ds_read_b128 v[116:119], v83 offset:18560
	ds_read_b128 v[120:123], v83 offset:18592
	ds_read_b128 v[124:127], v83 offset:27264
	ds_read_b128 v[130:133], v83 offset:27296
	v_mfma_f32_32x32x16_bf16 v[32:47], v[108:111], v[48:51], v[32:47]
	s_nop 11
	v_exp_f32_e32 v108, v32
	v_exp_f32_e32 v109, v33
	v_exp_f32_e32 v110, v34
	v_exp_f32_e32 v111, v35
	v_exp_f32_e32 v128, v36
	v_add_f32_e32 v95, v95, v108
	v_exp_f32_e32 v134, v37
	v_add_f32_e32 v95, v109, v95
	v_exp_f32_e32 v135, v38
	v_add_f32_e32 v95, v110, v95
	v_exp_f32_e32 v136, v39
	v_add_f32_e32 v95, v111, v95
	v_exp_f32_e32 v40, v40
	v_exp_f32_e32 v41, v41
	v_add_f32_e32 v95, v128, v95
	v_add_f32_e32 v95, v134, v95
	v_exp_f32_e32 v42, v42
	v_add_f32_e32 v95, v135, v95
	v_exp_f32_e32 v43, v43
	v_add_f32_e32 v95, v136, v95
	v_exp_f32_e32 v44, v44
	v_cvt_pk_bf16_f32 v36, v40, v41
	v_add_f32_e32 v40, v40, v95
	v_exp_f32_e32 v45, v45
	v_add_f32_e32 v40, v41, v40
	v_exp_f32_e32 v46, v46
	v_add_f32_e32 v40, v42, v40
	v_exp_f32_e32 v47, v47
	v_add_f32_e32 v40, v43, v40
	v_add_f32_e32 v40, v44, v40
	v_add_f32_e32 v40, v45, v40
	v_add_f32_e32 v40, v46, v40
	v_cvt_pk_bf16_f32 v32, v108, v109
	v_cvt_pk_bf16_f32 v33, v110, v111
	v_cvt_pk_bf16_f32 v37, v42, v43
	v_cvt_pk_bf16_f32 v34, v128, v134
	v_cvt_pk_bf16_f32 v38, v44, v45
	v_cvt_pk_bf16_f32 v35, v135, v136
	v_cvt_pk_bf16_f32 v39, v46, v47
	v_add_f32_e32 v108, v47, v40
	s_waitcnt lgkmcnt(3)
	v_mfma_f32_32x32x16_bf16 v[16:31], v[116:119], v[138:141], v[16:31]
	s_waitcnt lgkmcnt(1)
	v_mfma_f32_32x32x16_bf16 v[0:15], v[124:127], v[138:141], v[0:15]
	v_mfma_f32_32x32x16_bf16 v[16:31], v[120:123], v[142:145], v[16:31]
	s_waitcnt lgkmcnt(0)
	v_mfma_f32_32x32x16_bf16 v[0:15], v[130:133], v[142:145], v[0:15]
	ds_read_b128 v[40:43], v83 offset:18624
	v_add_u32_e32 v95, 0x11800, v81
	s_waitcnt lgkmcnt(0)
	v_mfma_f32_32x32x16_bf16 v[16:31], v[40:43], v[32:35], v[16:31]
	ds_read_b128 v[40:43], v83 offset:27328
	s_waitcnt lgkmcnt(0)
	v_mfma_f32_32x32x16_bf16 v[0:15], v[40:43], v[32:35], v[0:15]
	ds_read_b128 v[32:35], v83 offset:18656
	s_waitcnt lgkmcnt(0)
	v_mfma_f32_32x32x16_bf16 v[16:31], v[32:35], v[36:39], v[16:31]
	ds_read_b128 v[32:35], v83 offset:27360
	s_waitcnt vmcnt(3)
	ds_write_b128 v95, v[64:67]
	v_add_u32_e32 v64, 0x11800, v92
	s_waitcnt vmcnt(2)
	ds_write_b128 v64, v[72:75]
	s_waitcnt vmcnt(1)
	ds_write_b128 v94, v[68:71] offset:18432
	s_waitcnt vmcnt(0)
	ds_write_b128 v94, v[76:79] offset:27136
	s_waitcnt lgkmcnt(0)
	s_barrier
; #define KLOAD(kf_, base)                                                                       \
;   { _Pragma("unroll") for (int ks = 0; ks < NKS; ks++) kf_[ks] = *(const bf16x8*)((base) + kfo + ks * 32); }
; #define VLOAD(vf_, base)                                                                       \
;   { _Pragma("unroll") for (int q = 0; q < 4; q++) vf_[q] = *(const bf16x8*)((base) + vfo + (q >> 1) * 32 * VROW + (q & 1) * 32); }
; #define QKM(dst, kf_)                                                                          \
;   {                                                                                            \
;     _Pragma("unroll") for (int i = 0; i < 16; i++) dst[i] = 0.f;                               \
;     _Pragma("unroll") for (int ks = 0; ks < NKS; ks++) dst = MFMA(kf_[ks], qf[ks], dst);       \
;   }
; #define SB() __builtin_amdgcn_sched_barrier(0)
; template <int DK>
; DI void attn_core(const bf16x8 (&qf)[DK / 16], const short* Kg, const short* VTg, size_t ldvt, int ntiles, char* smem,
;                   f32x16 (&O)[2], float& lsum) {
;     ...
;   for (int t = 0; t < ntiles; t++) {
;     const int tn = t + 2 < ntiles ? t + 2 : ntiles - 1;
;     AGLOAD(tn);
;     const char* cur = smem + sc * ST;
;     const char* nxt = smem + sn * ST;
;     f32x16 Sn;
;     bf16x8 pa, pb, qa, qb;
;     bf16x8 kf[NKS], vf[4];
;     KLOAD(kf, cur + 32 * KROW);
;     SB();
;     SOFTMAX(Sc, pa, pb, l0);
;     SB();
;     QKM(Sn, kf);
;     SB();
;     KLOAD(kf, cur + 64 * KROW);
;     VLOAD(vf, cur);
;     SB();
;     SOFTMAX(Sn, qa, qb, l0);
;     SB();
;     QKM(Sc, kf);
;     PVM(vf, pa, pb);
;     SB();
;     KLOAD(kf, cur + 96 * KROW);
;     VLOAD(vf, cur + 64);
;     SB();
;     SOFTMAX(Sc, pa, pb, l0);
;     SB();
;     QKM(Sn, kf);
;     PVM(vf, qa, qb);
;     SB();
;     KLOAD(kf, nxt);
;     VLOAD(vf, cur + 128);
;     SB();
;     SOFTMAX(Sn, qa, qb, l0);
;     SB();
;     QKM(Sc, kf);
;     PVM(vf, pa, pb);
;     SB();
;     VLOAD(vf, cur + 192);
;     PVM(vf, qa, qb);
	v_mfma_f32_32x32x16_bf16 v[0:15], v[32:35], v[36:39], v[0:15]
	v_mfma_f32_32x32x16_bf16 v[32:47], v[96:99], v[60:63], 0
	v_mfma_f32_32x32x16_bf16 v[32:47], v[100:103], v[56:59], v[32:47]
	ds_read_b128 v[84:87], v93 offset:40448
	ds_read_b128 v[88:91], v93 offset:40480
	ds_read_b128 v[94:97], v93 offset:40512
	ds_read_b128 v[98:101], v93 offset:40544
	v_mfma_f32_32x32x16_bf16 v[32:47], v[104:107], v[52:55], v[32:47]
	v_mfma_f32_32x32x16_bf16 v[32:47], v[112:115], v[48:51], v[32:47]
	s_nop 11
	v_exp_f32_e32 v32, v32
	v_exp_f32_e32 v33, v33
	v_exp_f32_e32 v34, v34
	v_exp_f32_e32 v35, v35
	v_add_f32_e32 v102, v108, v32
	v_exp_f32_e32 v36, v36
	v_add_f32_e32 v102, v33, v102
	v_exp_f32_e32 v37, v37
	v_add_f32_e32 v102, v34, v102
	v_exp_f32_e32 v38, v38
	v_add_f32_e32 v102, v35, v102
	v_exp_f32_e32 v39, v39
	v_add_f32_e32 v102, v36, v102
	v_exp_f32_e32 v40, v40
	v_add_f32_e32 v102, v37, v102
	v_exp_f32_e32 v41, v41
	v_add_f32_e32 v102, v38, v102
	v_exp_f32_e32 v42, v42
	v_add_f32_e32 v102, v39, v102
	v_exp_f32_e32 v43, v43
	v_add_f32_e32 v102, v40, v102
	v_exp_f32_e32 v44, v44
	v_add_f32_e32 v102, v41, v102
	v_exp_f32_e32 v45, v45
	v_add_f32_e32 v102, v42, v102
	v_exp_f32_e32 v46, v46
	v_add_f32_e32 v102, v43, v102
	v_exp_f32_e32 v47, v47
	v_add_f32_e32 v102, v44, v102
	v_add_f32_e32 v102, v45, v102
	v_add_f32_e32 v102, v46, v102
	v_add_f32_e32 v126, v47, v102
	v_cvt_pk_bf16_f32 v102, v32, v33
	v_cvt_pk_bf16_f32 v106, v40, v41
	v_cvt_pk_bf16_f32 v103, v34, v35
	v_cvt_pk_bf16_f32 v107, v42, v43
	v_cvt_pk_bf16_f32 v104, v36, v37
	v_cvt_pk_bf16_f32 v108, v44, v45
	v_cvt_pk_bf16_f32 v105, v38, v39
	v_cvt_pk_bf16_f32 v109, v46, v47
	s_waitcnt lgkmcnt(3)
	v_mfma_f32_32x32x16_bf16 v[32:47], v[84:87], v[60:63], 0
	s_waitcnt lgkmcnt(2)
	v_mfma_f32_32x32x16_bf16 v[32:47], v[88:91], v[56:59], v[32:47]
	s_waitcnt lgkmcnt(1)
	v_mfma_f32_32x32x16_bf16 v[32:47], v[94:97], v[52:55], v[32:47]
	s_waitcnt lgkmcnt(0)
	v_mfma_f32_32x32x16_bf16 v[32:47], v[98:101], v[48:51], v[32:47]
	ds_read_b128 v[84:87], v93 offset:45056
	ds_read_b128 v[88:91], v93 offset:45088
	ds_read_b128 v[94:97], v93 offset:45120
	ds_read_b128 v[98:101], v93 offset:45152
	ds_read_b128 v[110:113], v83 offset:54272
	ds_read_b128 v[114:117], v83 offset:54304
	ds_read_b128 v[118:121], v83 offset:62976
	ds_read_b128 v[122:125], v83 offset:63008
	s_nop 3
	v_exp_f32_e32 v32, v32
	v_exp_f32_e32 v33, v33
	v_exp_f32_e32 v34, v34
	v_exp_f32_e32 v35, v35
	v_add_f32_e32 v126, v126, v32
	v_exp_f32_e32 v36, v36
	v_add_f32_e32 v126, v33, v126
	v_exp_f32_e32 v37, v37
	v_add_f32_e32 v126, v34, v126
	v_exp_f32_e32 v38, v38
	v_add_f32_e32 v126, v35, v126
	v_exp_f32_e32 v39, v39
	v_add_f32_e32 v126, v36, v126
	v_exp_f32_e32 v40, v40
	v_add_f32_e32 v126, v37, v126
	v_exp_f32_e32 v41, v41
	v_add_f32_e32 v126, v38, v126
	v_exp_f32_e32 v42, v42
	v_add_f32_e32 v126, v39, v126
	v_exp_f32_e32 v43, v43
	v_add_f32_e32 v126, v40, v126
	v_exp_f32_e32 v44, v44
	v_add_f32_e32 v126, v41, v126
	v_exp_f32_e32 v45, v45
	v_add_f32_e32 v126, v42, v126
	v_exp_f32_e32 v46, v46
	v_add_f32_e32 v126, v43, v126
	v_exp_f32_e32 v47, v47
	v_add_f32_e32 v126, v44, v126
	v_add_f32_e32 v126, v45, v126
	v_add_f32_e32 v126, v46, v126
	v_add_f32_e32 v126, v47, v126
	v_cvt_pk_bf16_f32 v130, v32, v33
	v_cvt_pk_bf16_f32 v134, v40, v41
	v_cvt_pk_bf16_f32 v131, v34, v35
	v_cvt_pk_bf16_f32 v135, v42, v43
	v_cvt_pk_bf16_f32 v132, v36, v37
	v_cvt_pk_bf16_f32 v136, v44, v45
	v_cvt_pk_bf16_f32 v133, v38, v39
	v_cvt_pk_bf16_f32 v137, v46, v47
	s_waitcnt lgkmcnt(7)
	v_mfma_f32_32x32x16_bf16 v[32:47], v[84:87], v[60:63], 0
	s_waitcnt lgkmcnt(6)
	v_mfma_f32_32x32x16_bf16 v[32:47], v[88:91], v[56:59], v[32:47]
	s_waitcnt lgkmcnt(5)
	v_mfma_f32_32x32x16_bf16 v[32:47], v[94:97], v[52:55], v[32:47]
	s_waitcnt lgkmcnt(3)
	v_mfma_f32_32x32x16_bf16 v[16:31], v[110:113], v[102:105], v[16:31]
	s_waitcnt lgkmcnt(1)
	v_mfma_f32_32x32x16_bf16 v[0:15], v[118:121], v[102:105], v[0:15]
	v_mfma_f32_32x32x16_bf16 v[32:47], v[98:101], v[48:51], v[32:47]
	v_mfma_f32_32x32x16_bf16 v[16:31], v[114:117], v[106:109], v[16:31]
	s_waitcnt lgkmcnt(0)
	v_mfma_f32_32x32x16_bf16 v[0:15], v[122:125], v[106:109], v[0:15]
	ds_read_b128 v[84:87], v93 offset:49664
	ds_read_b128 v[88:91], v93 offset:49696
	ds_read_b128 v[94:97], v93 offset:49728
	ds_read_b128 v[98:101], v93 offset:49760
	ds_read_b128 v[102:105], v83 offset:54336
	ds_read_b128 v[106:109], v83 offset:54368
	ds_read_b128 v[110:113], v83 offset:63040
	ds_read_b128 v[114:117], v83 offset:63072
	s_nop 0
	v_exp_f32_e32 v32, v32
	v_exp_f32_e32 v33, v33
	v_exp_f32_e32 v34, v34
	v_exp_f32_e32 v35, v35
	v_add_f32_e32 v93, v32, v126
	v_exp_f32_e32 v36, v36
	v_add_f32_e32 v93, v33, v93
	v_exp_f32_e32 v37, v37
	v_add_f32_e32 v93, v34, v93
	v_exp_f32_e32 v38, v38
	v_add_f32_e32 v93, v35, v93
	v_exp_f32_e32 v39, v39
	v_add_f32_e32 v93, v36, v93
	v_exp_f32_e32 v40, v40
	v_add_f32_e32 v93, v37, v93
	v_exp_f32_e32 v41, v41
	v_add_f32_e32 v93, v38, v93
	v_exp_f32_e32 v42, v42
	v_add_f32_e32 v93, v39, v93
	v_exp_f32_e32 v43, v43
	v_add_f32_e32 v93, v40, v93
	v_exp_f32_e32 v44, v44
	v_add_f32_e32 v93, v41, v93
	v_exp_f32_e32 v45, v45
	v_add_f32_e32 v93, v42, v93
	v_exp_f32_e32 v46, v46
	v_add_f32_e32 v93, v43, v93
	v_exp_f32_e32 v47, v47
	v_add_f32_e32 v93, v44, v93
	v_add_f32_e32 v93, v45, v93
	v_add_f32_e32 v93, v46, v93
	v_add_f32_e32 v93, v47, v93
	v_cvt_pk_bf16_f32 v118, v32, v33
	v_cvt_pk_bf16_f32 v122, v40, v41
	v_cvt_pk_bf16_f32 v119, v34, v35
	v_cvt_pk_bf16_f32 v123, v42, v43
	v_cvt_pk_bf16_f32 v120, v36, v37
	v_cvt_pk_bf16_f32 v124, v44, v45
	v_cvt_pk_bf16_f32 v121, v38, v39
	v_cvt_pk_bf16_f32 v125, v46, v47
	s_waitcnt lgkmcnt(3)
; #define VLOAD(vf_, base)                                                                       \
;   { _Pragma("unroll") for (int q = 0; q < 4; q++) vf_[q] = *(const bf16x8*)((base) + vfo + (q >> 1) * 32 * VROW + (q & 1) * 32); }
; #define QKM(dst, kf_)                                                                          \
;   {                                                                                            \
;     _Pragma("unroll") for (int i = 0; i < 16; i++) dst[i] = 0.f;                               \
;     _Pragma("unroll") for (int ks = 0; ks < NKS; ks++) dst = MFMA(kf_[ks], qf[ks], dst);       \
;   }
; #define SB() __builtin_amdgcn_sched_barrier(0)
; template <int DK>
; DI void attn_core(const bf16x8 (&qf)[DK / 16], const short* Kg, const short* VTg, size_t ldvt, int ntiles, char* smem,
;                   f32x16 (&O)[2], float& lsum) {
;     ...
;     SOFTMAX(Sn, qa, qb, l0);
;     SB();
;     QKM(Sc, kf);
;     PVM(vf, pa, pb);
;     SB();
;     VLOAD(vf, cur + 192);
;     PVM(vf, qa, qb);
;     ASTORE(sw);
;     __syncthreads();
	v_mfma_f32_32x32x16_bf16 v[16:31], v[102:105], v[130:133], v[16:31]
	s_waitcnt lgkmcnt(1)
	v_mfma_f32_32x32x16_bf16 v[0:15], v[110:113], v[130:133], v[0:15]
	v_mfma_f32_32x32x16_bf16 v[16:31], v[106:109], v[134:137], v[16:31]
	s_waitcnt lgkmcnt(0)
	v_mfma_f32_32x32x16_bf16 v[0:15], v[114:117], v[134:137], v[0:15]
	v_mfma_f32_32x32x16_bf16 v[32:47], v[84:87], v[60:63], 0
	v_mfma_f32_32x32x16_bf16 v[32:47], v[88:91], v[56:59], v[32:47]
	v_mfma_f32_32x32x16_bf16 v[32:47], v[94:97], v[52:55], v[32:47]
	ds_read_b128 v[52:55], v83 offset:54400
	ds_read_b128 v[56:59], v83 offset:54432
	ds_read_b128 v[60:63], v83 offset:63104
	ds_read_b128 v[84:87], v83 offset:63136
	v_mfma_f32_32x32x16_bf16 v[32:47], v[98:101], v[48:51], v[32:47]
	s_nop 11
	v_exp_f32_e32 v48, v32
	v_exp_f32_e32 v49, v33
	v_exp_f32_e32 v50, v34
	v_exp_f32_e32 v51, v35
	v_exp_f32_e32 v88, v36
	v_cvt_pk_bf16_f32 v32, v48, v49
	v_add_f32_e32 v48, v93, v48
	v_exp_f32_e32 v89, v37
	v_add_f32_e32 v48, v49, v48
	v_exp_f32_e32 v90, v38
	v_add_f32_e32 v48, v50, v48
	v_exp_f32_e32 v91, v39
	v_add_f32_e32 v48, v51, v48
	v_exp_f32_e32 v40, v40
	v_exp_f32_e32 v41, v41
	v_add_f32_e32 v48, v88, v48
	v_add_f32_e32 v48, v89, v48
	v_exp_f32_e32 v42, v42
	v_add_f32_e32 v48, v90, v48
	v_exp_f32_e32 v43, v43
	v_add_f32_e32 v48, v91, v48
	v_exp_f32_e32 v44, v44
	v_cvt_pk_bf16_f32 v36, v40, v41
	v_add_f32_e32 v40, v40, v48
	v_exp_f32_e32 v45, v45
	v_add_f32_e32 v40, v41, v40
	v_exp_f32_e32 v46, v46
	v_add_f32_e32 v40, v42, v40
	v_exp_f32_e32 v47, v47
	v_add_f32_e32 v40, v43, v40
	v_add_f32_e32 v40, v44, v40
	v_add_f32_e32 v40, v45, v40
	v_add_f32_e32 v40, v46, v40
	v_cvt_pk_bf16_f32 v33, v50, v51
	v_cvt_pk_bf16_f32 v37, v42, v43
	v_cvt_pk_bf16_f32 v34, v88, v89
	v_cvt_pk_bf16_f32 v38, v44, v45
	v_cvt_pk_bf16_f32 v35, v90, v91
	v_cvt_pk_bf16_f32 v39, v46, v47
	v_add_f32_e32 v88, v47, v40
	s_waitcnt lgkmcnt(3)
	v_mfma_f32_32x32x16_bf16 v[16:31], v[52:55], v[118:121], v[16:31]
	s_waitcnt lgkmcnt(1)
	v_mfma_f32_32x32x16_bf16 v[0:15], v[60:63], v[118:121], v[0:15]
	v_mfma_f32_32x32x16_bf16 v[16:31], v[56:59], v[122:125], v[16:31]
	s_waitcnt lgkmcnt(0)
	v_mfma_f32_32x32x16_bf16 v[0:15], v[84:87], v[122:125], v[0:15]
	ds_read_b128 v[40:43], v83 offset:54464
	ds_read_b128 v[44:47], v83 offset:54496
	ds_read_b128 v[48:51], v83 offset:63168
	ds_read_b128 v[52:55], v83 offset:63200
	v_mov_b32_e32 v60, v196
	s_waitcnt vmcnt(1)
	ds_write_b128 v81, v[76:79]
	ds_write_b128 v92, v[68:71]
	ds_write_b128 v82, v[64:67] offset:18432
	s_waitcnt vmcnt(0)
	ds_write_b128 v82, v[72:75] offset:27136
	s_waitcnt lgkmcnt(0)
	s_barrier
; DI int my_tid() { int t = threadIdx.x; asm volatile("" : "+v"(t)); return t; }
; DI float bf_lo(unsigned u) { return __uint_as_float(u << 16); }
; DI float bf_hi(unsigned u) { return __uint_as_float(u & 0xffff0000u); }
; DI void attn_store(const f32x16 (&O)[2], float lsum, int tok, int col0, const short* gate, short* o, char* smem) {
;   const int tid = my_tid(), lane = tid & 63, w = tid >> 6, r = lane & 31, h = lane >> 5;
;   float l = lsum + __shfl_xor(lsum, 32);
;   float inv = __builtin_amdgcn_rcpf(l);
;   float* pw = (float*)(smem + w * (32 * 68 * 4));
;   const int tokw = tok - r;
;   const int ch = lane & 7;
;   u32x4 gpre[4];
; #pragma unroll
;   for (int j = 0; j < 4; j++) gpre[j] = *(const u32x4*)(gate + (size_t)(tokw + j * 8 + (lane >> 3)) * 1024 + col0 + ch * 8);
; #pragma unroll
;   for (int dt = 0; dt < 2; dt++)
; #pragma unroll
;     for (int q = 0; q < 4; q++) {
;       f32x4 t = {O[dt][q * 4 + 0] * inv, O[dt][q * 4 + 1] * inv, O[dt][q * 4 + 2] * inv, O[dt][q * 4 + 3] * inv};
;       *(f32x4*)(pw + r * 68 + dt * 32 + 8 * q + 4 * h) = t;
;     }
;   asm volatile("s_waitcnt lgkmcnt(0)" ::: "memory");
; #pragma unroll
;   for (int j = 0; j < 4; j++) {
;     const int row = j * 8 + (lane >> 3);
;     const size_t g = (size_t)(tokw + row) * 1024 + col0 + ch * 8;
;     const u32x4 gv = gpre[j];
;     const f32x4 a = *(const f32x4*)(pw + row * 68 + ch * 8), c = *(const f32x4*)(pw + row * 68 + ch * 8 + 4);
;     u32x4 ov;
;     ov[0] = pack_bf16(a[0] * bf_lo(gv[0]), a[1] * bf_hi(gv[0]));
;     ov[1] = pack_bf16(a[2] * bf_lo(gv[1]), a[3] * bf_hi(gv[1]));
;     ov[2] = pack_bf16(c[0] * bf_lo(gv[2]), c[1] * bf_hi(gv[2]));
;     ov[3] = pack_bf16(c[2] * bf_lo(gv[3]), c[3] * bf_hi(gv[3]));
;     __builtin_nontemporal_store(ov, (u32x4*)(o + g));
;   }
;   __syncthreads();
; }
	v_mfma_f32_32x32x16_bf16 v[16:31], v[40:43], v[32:35], v[16:31]
	v_and_b32_e32 v61, 31, v60
	v_bfe_u32 v62, v60, 3, 3
	s_or_b32 s30, s30, 0x600
	s_movk_i32 s28, 0x2200
	s_mov_b64 s[42:43], 0
	v_mfma_f32_32x32x16_bf16 v[0:15], v[48:51], v[32:35], v[0:15]
	v_sub_u32_e32 v32, v80, v61
	v_add_u32_e32 v48, v62, v32
	v_lshlrev_b32_e32 v32, 3, v60
	v_and_b32_e32 v63, 56, v32
	v_lshlrev_b32_e32 v128, 1, v63
	v_ashrrev_i32_e32 v49, 31, v48
	v_lshl_add_u64 v[50:51], s[8:9], 0, v[128:129]
	v_lshlrev_b64 v[56:57], 11, v[48:49]
	v_lshl_add_u64 v[32:33], v[50:51], 0, v[56:57]
	v_lshl_add_u64 v[32:33], v[32:33], 0, s[30:31]
	global_load_dwordx4 v[32:35], v[32:33], off
	v_add_u32_e32 v40, 8, v48
	v_ashrrev_i32_e32 v41, 31, v40
	v_lshlrev_b64 v[58:59], 11, v[40:41]
	v_lshl_add_u64 v[40:41], v[50:51], 0, v[58:59]
	v_lshl_add_u64 v[40:41], v[40:41], 0, s[30:31]
	global_load_dwordx4 v[40:43], v[40:41], off
	v_mfma_f32_32x32x16_bf16 v[16:31], v[44:47], v[36:39], v[16:31]
	v_and_b32_e32 v45, 64, v200
	v_xor_b32_e32 v44, 32, v200
	v_add_u32_e32 v45, 64, v45
	v_cmp_lt_i32_e32 vcc, v44, v45
	s_nop 1
	v_cndmask_b32_e32 v44, v200, v44, vcc
	v_mfma_f32_32x32x16_bf16 v[0:15], v[52:55], v[36:39], v[0:15]
	v_lshrrev_b32_e32 v36, 6, v60
	v_mul_lo_u32 v55, v36, s28
	v_add_u32_e32 v36, 16, v48
	v_ashrrev_i32_e32 v37, 31, v36
	v_lshlrev_b64 v[52:53], 11, v[36:37]
	v_lshl_add_u64 v[36:37], v[50:51], 0, v[52:53]
	v_lshl_add_u64 v[36:37], v[36:37], 0, s[30:31]
	v_lshlrev_b32_e32 v44, 2, v44
	global_load_dwordx4 v[36:39], v[36:37], off
	ds_bpermute_b32 v44, v44, v88
	s_waitcnt lgkmcnt(0)
	v_add_f32_e32 v54, v88, v44
	v_add_u32_e32 v44, 24, v48
	v_ashrrev_i32_e32 v45, 31, v44
	v_lshlrev_b64 v[48:49], 11, v[44:45]
	v_lshl_add_u64 v[44:45], v[50:51], 0, v[48:49]
	v_lshl_add_u64 v[44:45], v[44:45], 0, s[30:31]
	global_load_dwordx4 v[44:47], v[44:45], off
	v_rcp_f32_e32 v50, v54
	v_lshrrev_b32_e32 v54, 1, v60
	v_mul_u32_u24_e32 v51, 0x110, v61
	v_and_b32_e32 v54, 16, v54
	v_add3_u32 v51, v55, v51, v54
	v_pk_mul_f32 v[16:17], v[16:17], v[50:51] op_sel_hi:[1,0]
	v_pk_mul_f32 v[18:19], v[18:19], v[50:51] op_sel_hi:[1,0]
	v_pk_mul_f32 v[0:1], v[0:1], v[50:51] op_sel_hi:[1,0]
	v_pk_mul_f32 v[2:3], v[2:3], v[50:51] op_sel_hi:[1,0]
	ds_write_b128 v51, v[16:19]
	v_pk_mul_f32 v[16:17], v[20:21], v[50:51] op_sel_hi:[1,0]
	v_pk_mul_f32 v[18:19], v[22:23], v[50:51] op_sel_hi:[1,0]
	ds_write_b128 v51, v[0:3] offset:128
	v_pk_mul_f32 v[0:1], v[4:5], v[50:51] op_sel_hi:[1,0]
	v_pk_mul_f32 v[2:3], v[6:7], v[50:51] op_sel_hi:[1,0]
	ds_write_b128 v51, v[16:19] offset:32
	v_pk_mul_f32 v[16:17], v[24:25], v[50:51] op_sel_hi:[1,0]
	v_pk_mul_f32 v[18:19], v[26:27], v[50:51] op_sel_hi:[1,0]
	ds_write_b128 v51, v[0:3] offset:160
	v_pk_mul_f32 v[0:1], v[8:9], v[50:51] op_sel_hi:[1,0]
	v_pk_mul_f32 v[2:3], v[10:11], v[50:51] op_sel_hi:[1,0]
	ds_write_b128 v51, v[16:19] offset:64
	v_pk_mul_f32 v[16:17], v[28:29], v[50:51] op_sel_hi:[1,0]
	v_pk_mul_f32 v[18:19], v[30:31], v[50:51] op_sel_hi:[1,0]
	ds_write_b128 v51, v[0:3] offset:192
	v_pk_mul_f32 v[0:1], v[12:13], v[50:51] op_sel_hi:[1,0]
	v_pk_mul_f32 v[2:3], v[14:15], v[50:51] op_sel_hi:[1,0]
	ds_write_b128 v51, v[16:19] offset:96
	ds_write_b128 v51, v[0:3] offset:224
	v_lshl_or_b32 v0, v63, 2, v55
	s_waitcnt lgkmcnt(0)
	v_mad_u32_u24 v12, v62, s16, v0
	ds_read_b128 v[0:3], v12
	ds_read_b128 v[4:7], v12 offset:16
	v_lshl_add_u64 v[8:9], s[14:15], 0, v[128:129]
	s_waitcnt vmcnt(3)
	v_lshlrev_b32_e32 v10, 16, v32
	v_and_b32_e32 v11, 0xffff0000, v32
	s_waitcnt lgkmcnt(1)
	v_pk_mul_f32 v[0:1], v[0:1], v[10:11]
	v_lshlrev_b32_e32 v10, 16, v33
	v_and_b32_e32 v11, 0xffff0000, v33
	v_pk_mul_f32 v[2:3], v[2:3], v[10:11]
	v_cvt_pk_bf16_f32 v0, v0, v1
	v_cvt_pk_bf16_f32 v1, v2, v3
	v_lshlrev_b32_e32 v2, 16, v34
	v_and_b32_e32 v3, 0xffff0000, v34
	s_waitcnt lgkmcnt(0)
	v_pk_mul_f32 v[2:3], v[4:5], v[2:3]
	v_lshlrev_b32_e32 v4, 16, v35
	v_and_b32_e32 v5, 0xffff0000, v35
	v_pk_mul_f32 v[4:5], v[6:7], v[4:5]
	v_cvt_pk_bf16_f32 v2, v2, v3
	v_cvt_pk_bf16_f32 v3, v4, v5
	v_lshl_add_u64 v[4:5], v[8:9], 0, v[56:57]
	v_lshl_add_u64 v[10:11], v[4:5], 0, s[30:31]
	ds_read_b128 v[4:7], v12 offset:2176
	global_store_dwordx4 v[10:11], v[0:3], off nt
	ds_read_b128 v[0:3], v12 offset:2192
	s_waitcnt vmcnt(3)
	v_lshlrev_b32_e32 v10, 16, v40
	v_and_b32_e32 v11, 0xffff0000, v40
	s_waitcnt lgkmcnt(1)
	v_pk_mul_f32 v[4:5], v[4:5], v[10:11]
	v_lshlrev_b32_e32 v10, 16, v41
	v_and_b32_e32 v11, 0xffff0000, v41
	v_pk_mul_f32 v[6:7], v[6:7], v[10:11]
	v_cvt_pk_bf16_f32 v4, v4, v5
	v_cvt_pk_bf16_f32 v5, v6, v7
	v_lshlrev_b32_e32 v6, 16, v42
	v_and_b32_e32 v7, 0xffff0000, v42
	s_waitcnt lgkmcnt(0)
	v_pk_mul_f32 v[0:1], v[0:1], v[6:7]
	s_nop 0
	v_cvt_pk_bf16_f32 v6, v0, v1
	v_lshlrev_b32_e32 v0, 16, v43
	v_and_b32_e32 v1, 0xffff0000, v43
	v_pk_mul_f32 v[0:1], v[2:3], v[0:1]
	s_nop 0
	v_cvt_pk_bf16_f32 v7, v0, v1
	v_lshl_add_u64 v[0:1], v[8:9], 0, v[58:59]
	v_lshl_add_u64 v[10:11], v[0:1], 0, s[30:31]
	ds_read_b128 v[0:3], v12 offset:4352
	global_store_dwordx4 v[10:11], v[4:7], off nt
	ds_read_b128 v[4:7], v12 offset:4368
	s_waitcnt vmcnt(3)
	v_lshlrev_b32_e32 v10, 16, v36
	v_and_b32_e32 v11, 0xffff0000, v36
	s_waitcnt lgkmcnt(1)
	v_pk_mul_f32 v[0:1], v[0:1], v[10:11]
	v_lshlrev_b32_e32 v10, 16, v37
	v_and_b32_e32 v11, 0xffff0000, v37
	v_pk_mul_f32 v[2:3], v[2:3], v[10:11]
	v_cvt_pk_bf16_f32 v0, v0, v1
	v_cvt_pk_bf16_f32 v1, v2, v3
	v_lshlrev_b32_e32 v2, 16, v38
	v_and_b32_e32 v3, 0xffff0000, v38
	s_waitcnt lgkmcnt(0)
	v_pk_mul_f32 v[2:3], v[4:5], v[2:3]
	v_lshlrev_b32_e32 v4, 16, v39
	v_and_b32_e32 v5, 0xffff0000, v39
	v_pk_mul_f32 v[4:5], v[6:7], v[4:5]
	v_cvt_pk_bf16_f32 v2, v2, v3
	v_cvt_pk_bf16_f32 v3, v4, v5
	v_lshl_add_u64 v[4:5], v[8:9], 0, v[52:53]
	v_lshl_add_u64 v[10:11], v[4:5], 0, s[30:31]
	ds_read_b128 v[4:7], v12 offset:6528
	global_store_dwordx4 v[10:11], v[0:3], off nt
	ds_read_b128 v[0:3], v12 offset:6544
	s_waitcnt vmcnt(3)
	v_lshlrev_b32_e32 v10, 16, v44
	v_and_b32_e32 v11, 0xffff0000, v44
	s_waitcnt lgkmcnt(1)
	v_pk_mul_f32 v[4:5], v[4:5], v[10:11]
	v_lshlrev_b32_e32 v10, 16, v45
	v_and_b32_e32 v11, 0xffff0000, v45
	v_pk_mul_f32 v[6:7], v[6:7], v[10:11]
	v_cvt_pk_bf16_f32 v4, v4, v5
	v_cvt_pk_bf16_f32 v5, v6, v7
	v_lshlrev_b32_e32 v6, 16, v46
	v_and_b32_e32 v7, 0xffff0000, v46
	s_waitcnt lgkmcnt(0)
	v_pk_mul_f32 v[0:1], v[0:1], v[6:7]
	s_nop 0
	v_cvt_pk_bf16_f32 v6, v0, v1
	v_lshlrev_b32_e32 v0, 16, v47
	v_and_b32_e32 v1, 0xffff0000, v47
	v_pk_mul_f32 v[0:1], v[2:3], v[0:1]
	s_nop 0
	v_cvt_pk_bf16_f32 v7, v0, v1
	v_lshl_add_u64 v[0:1], v[8:9], 0, v[48:49]
	v_lshl_add_u64 v[0:1], v[0:1], 0, s[30:31]
	global_store_dwordx4 v[0:1], v[4:7], off nt
	s_barrier

; DI int my_tid() { int t = threadIdx.x; asm volatile("" : "+v"(t)); return t; }
; #define KLOAD(kf_, base)                                                                       \
;   { _Pragma("unroll") for (int ks = 0; ks < NKS; ks++) kf_[ks] = *(const bf16x8*)((base) + kfo + ks * 32); }
; #define QKM(dst, kf_)                                                                          \
;   {                                                                                            \
;     _Pragma("unroll") for (int i = 0; i < 16; i++) dst[i] = 0.f;                               \
;     _Pragma("unroll") for (int ks = 0; ks < NKS; ks++) dst = MFMA(kf_[ks], qf[ks], dst);       \
;   }
; template <int DK>
; DI void attn_core(const bf16x8 (&qf)[DK / 16], const short* Kg, const short* VTg, size_t ldvt, int ntiles, char* smem,
;                   f32x16 (&O)[2], float& lsum) {
;     ...
;   for (int i = 0; i < NKC; i++) { int c = tid + 512 * i; koff[i] = (c / KCH) * KROW + (c % KCH) * 16; }
;   const int vrow = tid >> 4, vcol = tid & 15;
;   const short* vg = VTg + (size_t)vrow * ldvt + vcol * 8;
;   const int voff = KT_BYTES + vrow * VROW + vcol * 16;
; #pragma unroll
;   for (int i = 0; i < 16; i++) { O[0][i] = 0.f; O[1][i] = 0.f; }
;   float l0 = 0.f;
;     ...
;   const int kfo = pr * KROW + h * 16;
;   const int vfo = KT_BYTES + r * VROW + h * 16;
;   AGLOAD(0);
;   ASTORE(0);
;   AGLOAD(ntiles > 1 ? 1 : 0);
;   ASTORE(1);
;   __syncthreads();
;   f32x16 Sc;
;   {
;     bf16x8 kf[NKS];
;     KLOAD(kf, smem);
;     QKM(Sc, kf);
; DI void memattn_item(PRef p, int layer, int mt, int head, char* smem) {
;   const int tid = my_tid(), lane = tid & 63, w = tid >> 6, r = lane & 31, h = lane >> 5;
;   const int tok = mt * 256 + w * 32 + r;
;   const int seq = tok_seq(mt * 256);
;   const short* Q = (const short*)(p.ws + OFF_QMEM);
;   bf16x8 qf[4];
; #pragma unroll
;   for (int ks = 0; ks < 4; ks++) qf[ks] = *(const bf16x8*)(Q + (size_t)tok * 256 + head * 64 + ks * 16 + 8 * h);
;   const size_t hb = ((size_t)(layer * NSEQ + seq) * 4 + head) * 256 * 64;
.LBB0_175:
	v_mov_b32_e32 v2, v196
	s_ashr_i32 s14, s16, 2
	s_lshl_b32 s15, s14, 8
	v_ashrrev_i32_e32 v0, 1, v2
	v_and_b32_e32 v0, 0xffffffe0, v0
	v_add_u32_e32 v0, s15, v0
	v_and_or_b32 v80, v2, 31, v0
	v_ashrrev_i32_e32 v81, 31, v80
	s_and_b32 s20, s16, 3
	v_lshlrev_b64 v[0:1], 9, v[80:81]
	v_lshl_add_u64 v[0:1], s[4:5], 0, v[0:1]
	s_lshl_b32 s30, s20, 7
	v_lshrrev_b32_e32 v2, 1, v2
	v_lshl_add_u64 v[0:1], v[0:1], 0, s[30:31]
	s_waitcnt vmcnt(7)
	v_and_b32_e32 v128, 16, v2
	v_lshl_add_u64 v[0:1], v[0:1], 0, v[128:129]
	s_addk_i32 s15, 0xc000
	v_mov_b32_e32 v2, v196
	global_load_dwordx4 v[60:63], v[0:1], off
	global_load_dwordx4 v[56:59], v[0:1], off offset:32
	global_load_dwordx4 v[52:55], v[0:1], off offset:64
	global_load_dwordx4 v[48:51], v[0:1], off offset:96
	s_lshr_b32 s15, s15, 12
	s_add_i32 s15, s15, 1
	v_lshlrev_b32_e32 v0, 1, v2
	v_and_b32_e32 v10, 8, v0
	v_ashrrev_i32_e32 v0, 31, v2
	s_cmp_gt_i32 s14, 63
	v_lshrrev_b32_e32 v0, 29, v0
	s_cselect_b32 s14, s15, 0
	s_mul_i32 s15, s28, 17
	v_add_u32_e32 v0, v2, v0
	s_add_i32 s14, s14, s15
	s_mov_b32 s15, s31
	v_lshrrev_b32_e32 v0, 3, v0
	s_lshl_b64 s[18:19], s[14:15], 17
	s_lshl_b32 s14, s20, 15
	v_add_lshl_u32 v81, v0, v2, 4
	v_add_u32_e32 v0, 0x200, v2
	s_or_b32 s18, s18, s14
	v_ashrrev_i32_e32 v1, 31, v0
	v_lshlrev_b32_e32 v4, 4, v2
	s_add_u32 s14, s10, s18
	v_lshrrev_b32_e32 v1, 29, v1
	v_and_b32_e32 v128, 0xf0, v4
	v_lshlrev_b32_e32 v4, 3, v2
	s_addc_u32 s15, s11, s19
	v_add_u32_e32 v1, v0, v1
	v_ashrrev_i32_e32 v16, 4, v2
	v_ashrrev_i32_e32 v5, 31, v4
	s_add_u32 s18, s12, s18
	v_lshrrev_b32_e32 v1, 3, v1
	v_ashrrev_i32_e32 v17, 31, v16
	v_lshlrev_b64 v[18:19], 1, v[4:5]
	v_add_u32_e32 v4, 0x1000, v4
	s_addc_u32 s19, s13, s19
	v_add_lshl_u32 v92, v1, v0, 4
	v_lshlrev_b64 v[0:1], 9, v[16:17]
	v_ashrrev_i32_e32 v5, 31, v4
	v_lshrrev_b32_e32 v3, 1, v2
	v_lshl_add_u64 v[8:9], s[18:19], 0, v[0:1]
	v_lshl_add_u64 v[0:1], s[14:15], 0, v[18:19]
	v_lshlrev_b64 v[20:21], 1, v[4:5]
	v_and_b32_e32 v32, 31, v2
	v_and_b32_e32 v11, 4, v3
	v_and_b32_e32 v12, 19, v2
	v_and_b32_e32 v33, 16, v3
	global_load_dwordx4 v[0:3], v[0:1], off
	v_lshl_add_u64 v[4:5], s[14:15], 0, v[20:21]
	v_lshl_add_u64 v[84:85], v[8:9], 0, v[128:129]
	global_load_dwordx4 v[4:7], v[4:5], off
	v_or3_b32 v10, v12, v10, v11
	v_add_co_u32_e32 v86, vcc, s84, v84
	v_mad_u32_u24 v93, v10, s21, v33
	global_load_dwordx4 v[8:11], v[84:85], off
	v_addc_co_u32_e32 v87, vcc, 0, v85, vcc
	global_load_dwordx4 v[12:15], v[86:87], off
	s_add_u32 s14, s14, 0x4000
	s_addc_u32 s15, s15, 0
	v_mad_u64_u32 v[82:83], s[18:19], v16, s36, v[128:129]
	v_lshl_add_u64 v[88:89], s[14:15], 0, v[18:19]
	v_lshl_add_u64 v[90:91], s[14:15], 0, v[20:21]
	v_add_u32_e32 v94, 0x11800, v82
	global_load_dwordx4 v[64:67], v[88:89], off
	global_load_dwordx4 v[68:71], v[90:91], off
	global_load_dwordx4 v[72:75], v[84:85], off offset:256
	global_load_dwordx4 v[76:79], v[86:87], off offset:256
	s_waitcnt vmcnt(7)
	ds_write_b128 v81, v[0:3]
	s_waitcnt vmcnt(6)
	ds_write_b128 v92, v[4:7]
	s_waitcnt vmcnt(5)
	ds_write_b128 v82, v[8:11] offset:18432
	s_waitcnt vmcnt(4)
	ds_write_b128 v82, v[12:15] offset:27136
	s_waitcnt vmcnt(3)
	ds_write_b128 v81, v[64:67] offset:35840
	s_waitcnt vmcnt(2)
	ds_write_b128 v92, v[68:71] offset:35840
	s_waitcnt vmcnt(1)
	ds_write_b128 v82, v[72:75] offset:54272
	s_waitcnt vmcnt(0)
	ds_write_b128 v82, v[76:79] offset:62976
	s_waitcnt lgkmcnt(0)
	s_barrier
	ds_read_b128 v[0:3], v93
	ds_read_b128 v[16:19], v93 offset:32
	ds_read_b128 v[20:23], v93 offset:64
	ds_read_b128 v[24:27], v93 offset:96
	s_waitcnt lgkmcnt(3)
	v_mfma_f32_32x32x16_bf16 v[0:15], v[0:3], v[60:63], 0
	s_waitcnt lgkmcnt(2)
	v_mfma_f32_32x32x16_bf16 v[0:15], v[16:19], v[56:59], v[0:15]
	s_waitcnt lgkmcnt(1)
	v_mfma_f32_32x32x16_bf16 v[0:15], v[20:23], v[52:55], v[0:15]
	s_waitcnt lgkmcnt(0)
	v_mfma_f32_32x32x16_bf16 v[0:15], v[24:27], v[48:51], v[0:15]
	ds_read_b128 v[16:19], v93 offset:4608
	ds_read_b128 v[20:23], v93 offset:4640
	ds_read_b128 v[24:27], v93 offset:4672
	ds_read_b128 v[28:31], v93 offset:4704
	s_nop 7
	v_exp_f32_e32 v0, v0
	v_exp_f32_e32 v1, v1
	v_exp_f32_e32 v2, v2
	v_exp_f32_e32 v3, v3
	v_add_f32_e32 v34, 0, v0
	v_exp_f32_e32 v4, v4
	v_add_f32_e32 v34, v1, v34
	v_exp_f32_e32 v5, v5
	v_add_f32_e32 v34, v2, v34
	v_exp_f32_e32 v6, v6
	v_add_f32_e32 v34, v3, v34
	v_exp_f32_e32 v7, v7
	v_add_f32_e32 v34, v4, v34
	v_exp_f32_e32 v8, v8
	v_add_f32_e32 v34, v5, v34
	v_exp_f32_e32 v9, v9
	v_add_f32_e32 v34, v6, v34
	v_exp_f32_e32 v10, v10
	v_add_f32_e32 v34, v7, v34
	v_exp_f32_e32 v11, v11
	v_add_f32_e32 v34, v8, v34
	v_exp_f32_e32 v12, v12
	v_add_f32_e32 v34, v9, v34
	v_exp_f32_e32 v13, v13
	v_add_f32_e32 v34, v10, v34
	v_exp_f32_e32 v14, v14
	v_add_f32_e32 v34, v11, v34
	v_exp_f32_e32 v15, v15
	v_add_f32_e32 v34, v12, v34
	v_add_f32_e32 v34, v13, v34
	v_add_f32_e32 v34, v14, v34
	v_add_f32_e32 v34, v15, v34
	v_cvt_pk_bf16_f32 v96, v0, v1
	v_cvt_pk_bf16_f32 v100, v8, v9
	v_cvt_pk_bf16_f32 v97, v2, v3
	v_cvt_pk_bf16_f32 v101, v10, v11
	v_cvt_pk_bf16_f32 v98, v4, v5
	v_cvt_pk_bf16_f32 v102, v12, v13
	v_cvt_pk_bf16_f32 v99, v6, v7
	v_cvt_pk_bf16_f32 v103, v14, v15
	s_waitcnt lgkmcnt(3)
	v_mfma_f32_32x32x16_bf16 v[0:15], v[16:19], v[60:63], 0
	s_waitcnt lgkmcnt(2)
	v_mfma_f32_32x32x16_bf16 v[0:15], v[20:23], v[56:59], v[0:15]
	s_waitcnt lgkmcnt(1)
	v_mfma_f32_32x32x16_bf16 v[0:15], v[24:27], v[52:55], v[0:15]
	s_waitcnt lgkmcnt(0)
; #define KLOAD(kf_, base)                                                                       \
;   { _Pragma("unroll") for (int ks = 0; ks < NKS; ks++) kf_[ks] = *(const bf16x8*)((base) + kfo + ks * 32); }
; #define VLOAD(vf_, base)                                                                       \
;   { _Pragma("unroll") for (int q = 0; q < 4; q++) vf_[q] = *(const bf16x8*)((base) + vfo + (q >> 1) * 32 * VROW + (q & 1) * 32); }
; #define QKM(dst, kf_)                                                                          \
;   {                                                                                            \
;     _Pragma("unroll") for (int i = 0; i < 16; i++) dst[i] = 0.f;                               \
;     _Pragma("unroll") for (int ks = 0; ks < NKS; ks++) dst = MFMA(kf_[ks], qf[ks], dst);       \
;   }
; #define SB() __builtin_amdgcn_sched_barrier(0)
; template <int DK>
; DI void attn_core(const bf16x8 (&qf)[DK / 16], const short* Kg, const short* VTg, size_t ldvt, int ntiles, char* smem,
;                   f32x16 (&O)[2], float& lsum) {
;     ...
;     KLOAD(kf, cur + 32 * KROW);
;     SB();
;     SOFTMAX(Sc, pa, pb, l0);
;     SB();
;     QKM(Sn, kf);
;     SB();
;     KLOAD(kf, cur + 64 * KROW);
;     VLOAD(vf, cur);
;     SB();
;     SOFTMAX(Sn, qa, qb, l0);
;     SB();
;     QKM(Sc, kf);
;     PVM(vf, pa, pb);
;     SB();
;     KLOAD(kf, cur + 96 * KROW);
;     VLOAD(vf, cur + 64);
;     SB();
;     SOFTMAX(Sc, pa, pb, l0);
;     SB();
;     QKM(Sn, kf);
;     PVM(vf, qa, qb);
;     SB();
;     KLOAD(kf, nxt);
;     VLOAD(vf, cur + 128);
;     SB();
;     SOFTMAX(Sn, qa, qb, l0);
;     SB();
;     QKM(Sc, kf);
;     PVM(vf, pa, pb);
;     SB();
;     VLOAD(vf, cur + 192);
;     PVM(vf, qa, qb);
;     ASTORE(sw);
;     __syncthreads();
	v_mfma_f32_32x32x16_bf16 v[0:15], v[28:31], v[48:51], v[0:15]
	v_mad_u32_u24 v83, v32, s36, v33
	ds_read_b128 v[16:19], v93 offset:9216
	ds_read_b128 v[20:23], v93 offset:9248
	ds_read_b128 v[24:27], v93 offset:9280
	ds_read_b128 v[28:31], v93 offset:9312
	ds_read_b128 v[104:107], v83 offset:18432
	ds_read_b128 v[108:111], v83 offset:18464
	ds_read_b128 v[112:115], v83 offset:27136
	ds_read_b128 v[116:119], v83 offset:27168
	s_nop 2
	v_exp_f32_e32 v0, v0
	v_exp_f32_e32 v1, v1
	v_exp_f32_e32 v2, v2
	v_exp_f32_e32 v3, v3
	v_add_f32_e32 v32, v0, v34
	v_exp_f32_e32 v4, v4
	v_add_f32_e32 v32, v1, v32
	v_exp_f32_e32 v5, v5
	v_add_f32_e32 v32, v2, v32
	v_exp_f32_e32 v6, v6
	v_add_f32_e32 v32, v3, v32
	v_exp_f32_e32 v7, v7
	v_add_f32_e32 v32, v4, v32
	v_exp_f32_e32 v8, v8
	v_add_f32_e32 v32, v5, v32
	v_exp_f32_e32 v9, v9
	v_add_f32_e32 v32, v6, v32
	v_exp_f32_e32 v10, v10
	v_add_f32_e32 v32, v7, v32
	v_exp_f32_e32 v11, v11
	v_add_f32_e32 v32, v8, v32
	v_exp_f32_e32 v12, v12
	v_add_f32_e32 v32, v9, v32
	v_exp_f32_e32 v13, v13
	v_add_f32_e32 v32, v10, v32
	v_exp_f32_e32 v14, v14
	v_add_f32_e32 v32, v11, v32
	v_exp_f32_e32 v15, v15
	v_add_f32_e32 v32, v12, v32
	v_add_f32_e32 v32, v13, v32
	v_add_f32_e32 v32, v14, v32
	v_add_f32_e32 v95, v15, v32
	v_cvt_pk_bf16_f32 v120, v0, v1
	v_cvt_pk_bf16_f32 v124, v8, v9
	v_cvt_pk_bf16_f32 v121, v2, v3
	v_cvt_pk_bf16_f32 v125, v10, v11
	v_cvt_pk_bf16_f32 v122, v4, v5
	v_cvt_pk_bf16_f32 v126, v12, v13
	v_cvt_pk_bf16_f32 v123, v6, v7
	v_cvt_pk_bf16_f32 v127, v14, v15
	s_waitcnt lgkmcnt(7)
	v_mfma_f32_32x32x16_bf16 v[32:47], v[16:19], v[60:63], 0
	s_waitcnt lgkmcnt(6)
	v_mfma_f32_32x32x16_bf16 v[32:47], v[20:23], v[56:59], v[32:47]
	s_waitcnt lgkmcnt(5)
	v_mfma_f32_32x32x16_bf16 v[32:47], v[24:27], v[52:55], v[32:47]
	s_waitcnt lgkmcnt(4)
	v_mfma_f32_32x32x16_bf16 v[32:47], v[28:31], v[48:51], v[32:47]
	s_waitcnt lgkmcnt(3)
	v_mfma_f32_32x32x16_bf16 v[16:31], v[104:107], v[96:99], 0
	s_waitcnt lgkmcnt(1)
	v_mfma_f32_32x32x16_bf16 v[0:15], v[112:115], v[96:99], 0
	v_mfma_f32_32x32x16_bf16 v[16:31], v[108:111], v[100:103], v[16:31]
	s_waitcnt lgkmcnt(0)
	v_mfma_f32_32x32x16_bf16 v[0:15], v[116:119], v[100:103], v[0:15]
	ds_read_b128 v[96:99], v93 offset:13824
	ds_read_b128 v[100:103], v93 offset:13856
	ds_read_b128 v[104:107], v93 offset:13888
	ds_read_b128 v[108:111], v93 offset:13920
	ds_read_b128 v[112:115], v83 offset:18496
	ds_read_b128 v[116:119], v83 offset:18528
	ds_read_b128 v[130:133], v83 offset:27200
	ds_read_b128 v[134:137], v83 offset:27232
	v_exp_f32_e32 v32, v32
	v_exp_f32_e32 v33, v33
	v_exp_f32_e32 v34, v34
	v_exp_f32_e32 v35, v35
	v_add_f32_e32 v95, v32, v95
	v_exp_f32_e32 v36, v36
	v_add_f32_e32 v95, v33, v95
	v_exp_f32_e32 v37, v37
	v_add_f32_e32 v95, v34, v95
	v_exp_f32_e32 v38, v38
	v_add_f32_e32 v95, v35, v95
	v_exp_f32_e32 v39, v39
	v_add_f32_e32 v95, v36, v95
	v_exp_f32_e32 v40, v40
	v_add_f32_e32 v95, v37, v95
	v_exp_f32_e32 v41, v41
	v_add_f32_e32 v95, v38, v95
	v_exp_f32_e32 v42, v42
	v_add_f32_e32 v95, v39, v95
	v_exp_f32_e32 v43, v43
	v_add_f32_e32 v95, v40, v95
	v_exp_f32_e32 v44, v44
	v_add_f32_e32 v95, v41, v95
	v_exp_f32_e32 v45, v45
	v_add_f32_e32 v95, v42, v95
	v_exp_f32_e32 v46, v46
	v_add_f32_e32 v95, v43, v95
	v_exp_f32_e32 v47, v47
	v_add_f32_e32 v95, v44, v95
	v_add_f32_e32 v95, v45, v95
	v_add_f32_e32 v95, v46, v95
	v_add_f32_e32 v95, v47, v95
	v_cvt_pk_bf16_f32 v138, v32, v33
	v_cvt_pk_bf16_f32 v142, v40, v41
	v_cvt_pk_bf16_f32 v139, v34, v35
	v_cvt_pk_bf16_f32 v143, v42, v43
	v_cvt_pk_bf16_f32 v140, v36, v37
	v_cvt_pk_bf16_f32 v144, v44, v45
	v_cvt_pk_bf16_f32 v141, v38, v39
	v_cvt_pk_bf16_f32 v145, v46, v47
	s_waitcnt lgkmcnt(3)
	v_mfma_f32_32x32x16_bf16 v[16:31], v[112:115], v[120:123], v[16:31]
	s_waitcnt lgkmcnt(1)
	v_mfma_f32_32x32x16_bf16 v[0:15], v[130:133], v[120:123], v[0:15]
	v_mfma_f32_32x32x16_bf16 v[16:31], v[116:119], v[124:127], v[16:31]
	s_waitcnt lgkmcnt(0)
	v_mfma_f32_32x32x16_bf16 v[0:15], v[134:137], v[124:127], v[0:15]
	v_mfma_f32_32x32x16_bf16 v[32:47], v[96:99], v[60:63], 0
	v_mfma_f32_32x32x16_bf16 v[32:47], v[100:103], v[56:59], v[32:47]
	v_mfma_f32_32x32x16_bf16 v[32:47], v[104:107], v[52:55], v[32:47]
	ds_read_b128 v[96:99], v93 offset:35840
	ds_read_b128 v[100:103], v93 offset:35872
	ds_read_b128 v[104:107], v93 offset:35904
	ds_read_b128 v[112:115], v93 offset:35936
	ds_read_b128 v[116:119], v83 offset:18560
	ds_read_b128 v[120:123], v83 offset:18592
	ds_read_b128 v[124:127], v83 offset:27264
	ds_read_b128 v[130:133], v83 offset:27296
	v_mfma_f32_32x32x16_bf16 v[32:47], v[108:111], v[48:51], v[32:47]
	s_nop 11
	v_exp_f32_e32 v108, v32
	v_exp_f32_e32 v109, v33
	v_exp_f32_e32 v110, v34
	v_exp_f32_e32 v111, v35
	v_exp_f32_e32 v128, v36
	v_add_f32_e32 v95, v95, v108
	v_exp_f32_e32 v134, v37
	v_add_f32_e32 v95, v109, v95
	v_exp_f32_e32 v135, v38
	v_add_f32_e32 v95, v110, v95
	v_exp_f32_e32 v136, v39
	v_add_f32_e32 v95, v111, v95
	v_exp_f32_e32 v40, v40
	v_exp_f32_e32 v41, v41
	v_add_f32_e32 v95, v128, v95
	v_add_f32_e32 v95, v134, v95
	v_exp_f32_e32 v42, v42
	v_add_f32_e32 v95, v135, v95
	v_exp_f32_e32 v43, v43
	v_add_f32_e32 v95, v136, v95
	v_exp_f32_e32 v44, v44
	v_cvt_pk_bf16_f32 v36, v40, v41
	v_add_f32_e32 v40, v40, v95
	v_exp_f32_e32 v45, v45
	v_add_f32_e32 v40, v41, v40
	v_exp_f32_e32 v46, v46
	v_add_f32_e32 v40, v42, v40
	v_exp_f32_e32 v47, v47
	v_add_f32_e32 v40, v43, v40
	v_add_f32_e32 v40, v44, v40
	v_add_f32_e32 v40, v45, v40
	v_add_f32_e32 v40, v46, v40
	v_cvt_pk_bf16_f32 v32, v108, v109
	v_cvt_pk_bf16_f32 v33, v110, v111
	v_cvt_pk_bf16_f32 v37, v42, v43
	v_cvt_pk_bf16_f32 v34, v128, v134
	v_cvt_pk_bf16_f32 v38, v44, v45
	v_cvt_pk_bf16_f32 v35, v135, v136
	v_cvt_pk_bf16_f32 v39, v46, v47
	v_add_f32_e32 v108, v47, v40
	s_waitcnt lgkmcnt(3)
	v_mfma_f32_32x32x16_bf16 v[16:31], v[116:119], v[138:141], v[16:31]
	s_waitcnt lgkmcnt(1)
	v_mfma_f32_32x32x16_bf16 v[0:15], v[124:127], v[138:141], v[0:15]
	v_mfma_f32_32x32x16_bf16 v[16:31], v[120:123], v[142:145], v[16:31]
	s_waitcnt lgkmcnt(0)
	v_mfma_f32_32x32x16_bf16 v[0:15], v[130:133], v[142:145], v[0:15]
	ds_read_b128 v[40:43], v83 offset:18624
	v_add_u32_e32 v95, 0x11800, v81
	s_waitcnt lgkmcnt(0)
	v_mfma_f32_32x32x16_bf16 v[16:31], v[40:43], v[32:35], v[16:31]
	ds_read_b128 v[40:43], v83 offset:27328
	s_waitcnt lgkmcnt(0)
	v_mfma_f32_32x32x16_bf16 v[0:15], v[40:43], v[32:35], v[0:15]
	ds_read_b128 v[32:35], v83 offset:18656
	s_waitcnt lgkmcnt(0)
	v_mfma_f32_32x32x16_bf16 v[16:31], v[32:35], v[36:39], v[16:31]
	ds_read_b128 v[32:35], v83 offset:27360
	s_waitcnt vmcnt(3)
	ds_write_b128 v95, v[64:67]
	v_add_u32_e32 v64, 0x11800, v92
	s_waitcnt vmcnt(2)
	ds_write_b128 v64, v[72:75]
	s_waitcnt vmcnt(1)
	ds_write_b128 v94, v[68:71] offset:18432
	s_waitcnt vmcnt(0)
	ds_write_b128 v94, v[76:79] offset:27136
	s_waitcnt lgkmcnt(0)
	s_barrier
; #define KLOAD(kf_, base)                                                                       \
;   { _Pragma("unroll") for (int ks = 0; ks < NKS; ks++) kf_[ks] = *(const bf16x8*)((base) + kfo + ks * 32); }
; #define VLOAD(vf_, base)                                                                       \
;   { _Pragma("unroll") for (int q = 0; q < 4; q++) vf_[q] = *(const bf16x8*)((base) + vfo + (q >> 1) * 32 * VROW + (q & 1) * 32); }
; #define QKM(dst, kf_)                                                                          \
;   {                                                                                            \
;     _Pragma("unroll") for (int i = 0; i < 16; i++) dst[i] = 0.f;                               \
;     _Pragma("unroll") for (int ks = 0; ks < NKS; ks++) dst = MFMA(kf_[ks], qf[ks], dst);       \
;   }
; #define SB() __builtin_amdgcn_sched_barrier(0)
; template <int DK>
; DI void attn_core(const bf16x8 (&qf)[DK / 16], const short* Kg, const short* VTg, size_t ldvt, int ntiles, char* smem,
;                   f32x16 (&O)[2], float& lsum) {
;     ...
;   for (int t = 0; t < ntiles; t++) {
;     const int tn = t + 2 < ntiles ? t + 2 : ntiles - 1;
;     AGLOAD(tn);
;     const char* cur = smem + sc * ST;
;     const char* nxt = smem + sn * ST;
;     f32x16 Sn;
;     bf16x8 pa, pb, qa, qb;
;     bf16x8 kf[NKS], vf[4];
;     KLOAD(kf, cur + 32 * KROW);
;     SB();
;     SOFTMAX(Sc, pa, pb, l0);
;     SB();
;     QKM(Sn, kf);
;     SB();
;     KLOAD(kf, cur + 64 * KROW);
;     VLOAD(vf, cur);
;     SB();
;     SOFTMAX(Sn, qa, qb, l0);
;     SB();
;     QKM(Sc, kf);
;     PVM(vf, pa, pb);
;     SB();
;     KLOAD(kf, cur + 96 * KROW);
;     VLOAD(vf, cur + 64);
;     SB();
;     SOFTMAX(Sc, pa, pb, l0);
;     SB();
;     QKM(Sn, kf);
;     PVM(vf, qa, qb);
;     SB();
;     KLOAD(kf, nxt);
;     VLOAD(vf, cur + 128);
;     SB();
;     SOFTMAX(Sn, qa, qb, l0);
;     SB();
;     QKM(Sc, kf);
;     PVM(vf, pa, pb);
;     SB();
;     VLOAD(vf, cur + 192);
;     PVM(vf, qa, qb);
	v_mfma_f32_32x32x16_bf16 v[0:15], v[32:35], v[36:39], v[0:15]
	v_mfma_f32_32x32x16_bf16 v[32:47], v[96:99], v[60:63], 0
	v_mfma_f32_32x32x16_bf16 v[32:47], v[100:103], v[56:59], v[32:47]
	ds_read_b128 v[84:87], v93 offset:40448
	ds_read_b128 v[88:91], v93 offset:40480
	ds_read_b128 v[94:97], v93 offset:40512
	ds_read_b128 v[98:101], v93 offset:40544
	v_mfma_f32_32x32x16_bf16 v[32:47], v[104:107], v[52:55], v[32:47]
	v_mfma_f32_32x32x16_bf16 v[32:47], v[112:115], v[48:51], v[32:47]
	s_nop 11
	v_exp_f32_e32 v32, v32
	v_exp_f32_e32 v33, v33
	v_exp_f32_e32 v34, v34
	v_exp_f32_e32 v35, v35
	v_add_f32_e32 v102, v108, v32
	v_exp_f32_e32 v36, v36
	v_add_f32_e32 v102, v33, v102
	v_exp_f32_e32 v37, v37
	v_add_f32_e32 v102, v34, v102
	v_exp_f32_e32 v38, v38
	v_add_f32_e32 v102, v35, v102
	v_exp_f32_e32 v39, v39
	v_add_f32_e32 v102, v36, v102
	v_exp_f32_e32 v40, v40
	v_add_f32_e32 v102, v37, v102
	v_exp_f32_e32 v41, v41
	v_add_f32_e32 v102, v38, v102
	v_exp_f32_e32 v42, v42
	v_add_f32_e32 v102, v39, v102
	v_exp_f32_e32 v43, v43
	v_add_f32_e32 v102, v40, v102
	v_exp_f32_e32 v44, v44
	v_add_f32_e32 v102, v41, v102
	v_exp_f32_e32 v45, v45
	v_add_f32_e32 v102, v42, v102
	v_exp_f32_e32 v46, v46
	v_add_f32_e32 v102, v43, v102
	v_exp_f32_e32 v47, v47
	v_add_f32_e32 v102, v44, v102
	v_add_f32_e32 v102, v45, v102
	v_add_f32_e32 v102, v46, v102
	v_add_f32_e32 v126, v47, v102
	v_cvt_pk_bf16_f32 v102, v32, v33
	v_cvt_pk_bf16_f32 v106, v40, v41
	v_cvt_pk_bf16_f32 v103, v34, v35
	v_cvt_pk_bf16_f32 v107, v42, v43
	v_cvt_pk_bf16_f32 v104, v36, v37
	v_cvt_pk_bf16_f32 v108, v44, v45
	v_cvt_pk_bf16_f32 v105, v38, v39
	v_cvt_pk_bf16_f32 v109, v46, v47
	s_waitcnt lgkmcnt(3)
	v_mfma_f32_32x32x16_bf16 v[32:47], v[84:87], v[60:63], 0
	s_waitcnt lgkmcnt(2)
	v_mfma_f32_32x32x16_bf16 v[32:47], v[88:91], v[56:59], v[32:47]
	s_waitcnt lgkmcnt(1)
	v_mfma_f32_32x32x16_bf16 v[32:47], v[94:97], v[52:55], v[32:47]
	s_waitcnt lgkmcnt(0)
	v_mfma_f32_32x32x16_bf16 v[32:47], v[98:101], v[48:51], v[32:47]
	ds_read_b128 v[84:87], v93 offset:45056
	ds_read_b128 v[88:91], v93 offset:45088
	ds_read_b128 v[94:97], v93 offset:45120
	ds_read_b128 v[98:101], v93 offset:45152
	ds_read_b128 v[110:113], v83 offset:54272
	ds_read_b128 v[114:117], v83 offset:54304
	ds_read_b128 v[118:121], v83 offset:62976
	ds_read_b128 v[122:125], v83 offset:63008
	s_nop 3
	v_exp_f32_e32 v32, v32
	v_exp_f32_e32 v33, v33
	v_exp_f32_e32 v34, v34
	v_exp_f32_e32 v35, v35
	v_add_f32_e32 v126, v126, v32
	v_exp_f32_e32 v36, v36
	v_add_f32_e32 v126, v33, v126
	v_exp_f32_e32 v37, v37
	v_add_f32_e32 v126, v34, v126
	v_exp_f32_e32 v38, v38
	v_add_f32_e32 v126, v35, v126
	v_exp_f32_e32 v39, v39
	v_add_f32_e32 v126, v36, v126
	v_exp_f32_e32 v40, v40
	v_add_f32_e32 v126, v37, v126
	v_exp_f32_e32 v41, v41
	v_add_f32_e32 v126, v38, v126
	v_exp_f32_e32 v42, v42
	v_add_f32_e32 v126, v39, v126
	v_exp_f32_e32 v43, v43
	v_add_f32_e32 v126, v40, v126
	v_exp_f32_e32 v44, v44
	v_add_f32_e32 v126, v41, v126
	v_exp_f32_e32 v45, v45
	v_add_f32_e32 v126, v42, v126
	v_exp_f32_e32 v46, v46
	v_add_f32_e32 v126, v43, v126
	v_exp_f32_e32 v47, v47
	v_add_f32_e32 v126, v44, v126
	v_add_f32_e32 v126, v45, v126
	v_add_f32_e32 v126, v46, v126
	v_add_f32_e32 v126, v47, v126
	v_cvt_pk_bf16_f32 v130, v32, v33
	v_cvt_pk_bf16_f32 v134, v40, v41
	v_cvt_pk_bf16_f32 v131, v34, v35
	v_cvt_pk_bf16_f32 v135, v42, v43
	v_cvt_pk_bf16_f32 v132, v36, v37
	v_cvt_pk_bf16_f32 v136, v44, v45
	v_cvt_pk_bf16_f32 v133, v38, v39
	v_cvt_pk_bf16_f32 v137, v46, v47
	s_waitcnt lgkmcnt(7)
	v_mfma_f32_32x32x16_bf16 v[32:47], v[84:87], v[60:63], 0
	s_waitcnt lgkmcnt(6)
	v_mfma_f32_32x32x16_bf16 v[32:47], v[88:91], v[56:59], v[32:47]
	s_waitcnt lgkmcnt(5)
	v_mfma_f32_32x32x16_bf16 v[32:47], v[94:97], v[52:55], v[32:47]
	s_waitcnt lgkmcnt(3)
	v_mfma_f32_32x32x16_bf16 v[16:31], v[110:113], v[102:105], v[16:31]
	s_waitcnt lgkmcnt(1)
	v_mfma_f32_32x32x16_bf16 v[0:15], v[118:121], v[102:105], v[0:15]
	v_mfma_f32_32x32x16_bf16 v[32:47], v[98:101], v[48:51], v[32:47]
	v_mfma_f32_32x32x16_bf16 v[16:31], v[114:117], v[106:109], v[16:31]
	s_waitcnt lgkmcnt(0)
	v_mfma_f32_32x32x16_bf16 v[0:15], v[122:125], v[106:109], v[0:15]
	ds_read_b128 v[84:87], v93 offset:49664
	ds_read_b128 v[88:91], v93 offset:49696
	ds_read_b128 v[94:97], v93 offset:49728
	ds_read_b128 v[98:101], v93 offset:49760
	ds_read_b128 v[102:105], v83 offset:54336
	ds_read_b128 v[106:109], v83 offset:54368
	ds_read_b128 v[110:113], v83 offset:63040
	ds_read_b128 v[114:117], v83 offset:63072
	s_nop 0
	v_exp_f32_e32 v32, v32
	v_exp_f32_e32 v33, v33
	v_exp_f32_e32 v34, v34
	v_exp_f32_e32 v35, v35
	v_add_f32_e32 v93, v32, v126
	v_exp_f32_e32 v36, v36
	v_add_f32_e32 v93, v33, v93
	v_exp_f32_e32 v37, v37
	v_add_f32_e32 v93, v34, v93
	v_exp_f32_e32 v38, v38
	v_add_f32_e32 v93, v35, v93
	v_exp_f32_e32 v39, v39
	v_add_f32_e32 v93, v36, v93
	v_exp_f32_e32 v40, v40
	v_add_f32_e32 v93, v37, v93
	v_exp_f32_e32 v41, v41
	v_add_f32_e32 v93, v38, v93
	v_exp_f32_e32 v42, v42
	v_add_f32_e32 v93, v39, v93
	v_exp_f32_e32 v43, v43
	v_add_f32_e32 v93, v40, v93
	v_exp_f32_e32 v44, v44
	v_add_f32_e32 v93, v41, v93
	v_exp_f32_e32 v45, v45
	v_add_f32_e32 v93, v42, v93
	v_exp_f32_e32 v46, v46
	v_add_f32_e32 v93, v43, v93
	v_exp_f32_e32 v47, v47
	v_add_f32_e32 v93, v44, v93
	v_add_f32_e32 v93, v45, v93
	v_add_f32_e32 v93, v46, v93
	v_add_f32_e32 v93, v47, v93
	v_cvt_pk_bf16_f32 v118, v32, v33
	v_cvt_pk_bf16_f32 v122, v40, v41
	v_cvt_pk_bf16_f32 v119, v34, v35
	v_cvt_pk_bf16_f32 v123, v42, v43
	v_cvt_pk_bf16_f32 v120, v36, v37
	v_cvt_pk_bf16_f32 v124, v44, v45
	v_cvt_pk_bf16_f32 v121, v38, v39
	v_cvt_pk_bf16_f32 v125, v46, v47
	s_waitcnt lgkmcnt(3)
; #define VLOAD(vf_, base)                                                                       \
;   { _Pragma("unroll") for (int q = 0; q < 4; q++) vf_[q] = *(const bf16x8*)((base) + vfo + (q >> 1) * 32 * VROW + (q & 1) * 32); }
; #define QKM(dst, kf_)                                                                          \
;   {                                                                                            \
;     _Pragma("unroll") for (int i = 0; i < 16; i++) dst[i] = 0.f;                               \
;     _Pragma("unroll") for (int ks = 0; ks < NKS; ks++) dst = MFMA(kf_[ks], qf[ks], dst);       \
;   }
; #define SB() __builtin_amdgcn_sched_barrier(0)
; template <int DK>
; DI void attn_core(const bf16x8 (&qf)[DK / 16], const short* Kg, const short* VTg, size_t ldvt, int ntiles, char* smem,
;                   f32x16 (&O)[2], float& lsum) {
;     ...
;     SOFTMAX(Sn, qa, qb, l0);
;     SB();
;     QKM(Sc, kf);
;     PVM(vf, pa, pb);
;     SB();
;     VLOAD(vf, cur + 192);
;     PVM(vf, qa, qb);
;     ASTORE(sw);
;     __syncthreads();
	v_mfma_f32_32x32x16_bf16 v[16:31], v[102:105], v[130:133], v[16:31]
	s_waitcnt lgkmcnt(1)
	v_mfma_f32_32x32x16_bf16 v[0:15], v[110:113], v[130:133], v[0:15]
	v_mfma_f32_32x32x16_bf16 v[16:31], v[106:109], v[134:137], v[16:31]
	s_waitcnt lgkmcnt(0)
	v_mfma_f32_32x32x16_bf16 v[0:15], v[114:117], v[134:137], v[0:15]
	v_mfma_f32_32x32x16_bf16 v[32:47], v[84:87], v[60:63], 0
	v_mfma_f32_32x32x16_bf16 v[32:47], v[88:91], v[56:59], v[32:47]
	v_mfma_f32_32x32x16_bf16 v[32:47], v[94:97], v[52:55], v[32:47]
	ds_read_b128 v[52:55], v83 offset:54400
	ds_read_b128 v[56:59], v83 offset:54432
	ds_read_b128 v[60:63], v83 offset:63104
	ds_read_b128 v[84:87], v83 offset:63136
	v_mfma_f32_32x32x16_bf16 v[32:47], v[98:101], v[48:51], v[32:47]
	s_nop 11
	v_exp_f32_e32 v48, v32
	v_exp_f32_e32 v49, v33
	v_exp_f32_e32 v50, v34
	v_exp_f32_e32 v51, v35
	v_exp_f32_e32 v88, v36
	v_cvt_pk_bf16_f32 v32, v48, v49
	v_add_f32_e32 v48, v93, v48
	v_exp_f32_e32 v89, v37
	v_add_f32_e32 v48, v49, v48
	v_exp_f32_e32 v90, v38
	v_add_f32_e32 v48, v50, v48
	v_exp_f32_e32 v91, v39
	v_add_f32_e32 v48, v51, v48
	v_exp_f32_e32 v40, v40
	v_exp_f32_e32 v41, v41
	v_add_f32_e32 v48, v88, v48
	v_add_f32_e32 v48, v89, v48
	v_exp_f32_e32 v42, v42
	v_add_f32_e32 v48, v90, v48
	v_exp_f32_e32 v43, v43
	v_add_f32_e32 v48, v91, v48
	v_exp_f32_e32 v44, v44
	v_cvt_pk_bf16_f32 v36, v40, v41
	v_add_f32_e32 v40, v40, v48
	v_exp_f32_e32 v45, v45
	v_add_f32_e32 v40, v41, v40
	v_exp_f32_e32 v46, v46
	v_add_f32_e32 v40, v42, v40
	v_exp_f32_e32 v47, v47
	v_add_f32_e32 v40, v43, v40
	v_add_f32_e32 v40, v44, v40
	v_add_f32_e32 v40, v45, v40
	v_add_f32_e32 v40, v46, v40
	v_cvt_pk_bf16_f32 v33, v50, v51
	v_cvt_pk_bf16_f32 v37, v42, v43
	v_cvt_pk_bf16_f32 v34, v88, v89
	v_cvt_pk_bf16_f32 v38, v44, v45
	v_cvt_pk_bf16_f32 v35, v90, v91
	v_cvt_pk_bf16_f32 v39, v46, v47
	v_add_f32_e32 v88, v47, v40
	s_waitcnt lgkmcnt(3)
	v_mfma_f32_32x32x16_bf16 v[16:31], v[52:55], v[118:121], v[16:31]
	s_waitcnt lgkmcnt(1)
	v_mfma_f32_32x32x16_bf16 v[0:15], v[60:63], v[118:121], v[0:15]
	v_mfma_f32_32x32x16_bf16 v[16:31], v[56:59], v[122:125], v[16:31]
	s_waitcnt lgkmcnt(0)
	v_mfma_f32_32x32x16_bf16 v[0:15], v[84:87], v[122:125], v[0:15]
	ds_read_b128 v[40:43], v83 offset:54464
	ds_read_b128 v[44:47], v83 offset:54496
	ds_read_b128 v[48:51], v83 offset:63168
	ds_read_b128 v[52:55], v83 offset:63200
	v_mov_b32_e32 v60, v196
	s_waitcnt vmcnt(1)
	ds_write_b128 v81, v[76:79]
	ds_write_b128 v92, v[68:71]
	ds_write_b128 v82, v[64:67] offset:18432
	s_waitcnt vmcnt(0)
	ds_write_b128 v82, v[72:75] offset:27136
	s_waitcnt lgkmcnt(0)
	s_barrier
; DI int my_tid() { int t = threadIdx.x; asm volatile("" : "+v"(t)); return t; }
; DI float bf_lo(unsigned u) { return __uint_as_float(u << 16); }
; DI float bf_hi(unsigned u) { return __uint_as_float(u & 0xffff0000u); }
; DI void attn_store(const f32x16 (&O)[2], float lsum, int tok, int col0, const short* gate, short* o, char* smem) {
;   const int tid = my_tid(), lane = tid & 63, w = tid >> 6, r = lane & 31, h = lane >> 5;
;   float l = lsum + __shfl_xor(lsum, 32);
;   float inv = __builtin_amdgcn_rcpf(l);
;   float* pw = (float*)(smem + w * (32 * 68 * 4));
;   const int tokw = tok - r;
;   const int ch = lane & 7;
;   u32x4 gpre[4];
; #pragma unroll
;   for (int j = 0; j < 4; j++) gpre[j] = *(const u32x4*)(gate + (size_t)(tokw + j * 8 + (lane >> 3)) * 1024 + col0 + ch * 8);
; #pragma unroll
;   for (int dt = 0; dt < 2; dt++)
; #pragma unroll
;     for (int q = 0; q < 4; q++) {
;       f32x4 t = {O[dt][q * 4 + 0] * inv, O[dt][q * 4 + 1] * inv, O[dt][q * 4 + 2] * inv, O[dt][q * 4 + 3] * inv};
;       *(f32x4*)(pw + r * 68 + dt * 32 + 8 * q + 4 * h) = t;
;     }
;   asm volatile("s_waitcnt lgkmcnt(0)" ::: "memory");
; #pragma unroll
;   for (int j = 0; j < 4; j++) {
;     const int row = j * 8 + (lane >> 3);
;     const size_t g = (size_t)(tokw + row) * 1024 + col0 + ch * 8;
;     const u32x4 gv = gpre[j];
;     const f32x4 a = *(const f32x4*)(pw + row * 68 + ch * 8), c = *(const f32x4*)(pw + row * 68 + ch * 8 + 4);
;     u32x4 ov;
;     ov[0] = pack_bf16(a[0] * bf_lo(gv[0]), a[1] * bf_hi(gv[0]));
;     ov[1] = pack_bf16(a[2] * bf_lo(gv[1]), a[3] * bf_hi(gv[1]));
;     ov[2] = pack_bf16(c[0] * bf_lo(gv[2]), c[1] * bf_hi(gv[2]));
;     ov[3] = pack_bf16(c[2] * bf_lo(gv[3]), c[3] * bf_hi(gv[3]));
;     __builtin_nontemporal_store(ov, (u32x4*)(o + g));
;   }
;   __syncthreads();
; }
	v_mfma_f32_32x32x16_bf16 v[16:31], v[40:43], v[32:35], v[16:31]
	v_and_b32_e32 v61, 31, v60
	v_bfe_u32 v62, v60, 3, 3
	s_or_b32 s30, s30, 0x600
	s_add_i32 s16, s16, s51
	s_cmpk_gt_i32 s16, 0x4ff
	v_mfma_f32_32x32x16_bf16 v[0:15], v[48:51], v[32:35], v[0:15]
	v_sub_u32_e32 v32, v80, v61
	v_add_u32_e32 v48, v62, v32
	v_lshlrev_b32_e32 v32, 3, v60
	v_and_b32_e32 v63, 56, v32
	v_lshlrev_b32_e32 v128, 1, v63
	v_ashrrev_i32_e32 v49, 31, v48
	v_lshl_add_u64 v[50:51], s[6:7], 0, v[128:129]
	v_lshlrev_b64 v[56:57], 11, v[48:49]
	v_lshl_add_u64 v[32:33], v[50:51], 0, v[56:57]
	v_lshl_add_u64 v[32:33], v[32:33], 0, s[30:31]
	global_load_dwordx4 v[32:35], v[32:33], off
	v_add_u32_e32 v40, 8, v48
	v_ashrrev_i32_e32 v41, 31, v40
	v_lshlrev_b64 v[58:59], 11, v[40:41]
	v_lshl_add_u64 v[40:41], v[50:51], 0, v[58:59]
	v_lshl_add_u64 v[40:41], v[40:41], 0, s[30:31]
	global_load_dwordx4 v[40:43], v[40:41], off
	v_mfma_f32_32x32x16_bf16 v[16:31], v[44:47], v[36:39], v[16:31]
	v_and_b32_e32 v45, 64, v200
	v_xor_b32_e32 v44, 32, v200
	v_add_u32_e32 v45, 64, v45
	v_cmp_lt_i32_e32 vcc, v44, v45
	s_nop 1
	v_cndmask_b32_e32 v44, v200, v44, vcc
	v_mfma_f32_32x32x16_bf16 v[0:15], v[52:55], v[36:39], v[0:15]
	v_lshrrev_b32_e32 v36, 6, v60
	v_mul_lo_u32 v55, v36, s22
	v_add_u32_e32 v36, 16, v48
	v_ashrrev_i32_e32 v37, 31, v36
	v_lshlrev_b64 v[52:53], 11, v[36:37]
	v_lshl_add_u64 v[36:37], v[50:51], 0, v[52:53]
	v_lshl_add_u64 v[36:37], v[36:37], 0, s[30:31]
	v_lshlrev_b32_e32 v44, 2, v44
	global_load_dwordx4 v[36:39], v[36:37], off
	ds_bpermute_b32 v44, v44, v88
	s_waitcnt lgkmcnt(0)
	v_add_f32_e32 v54, v88, v44
	v_add_u32_e32 v44, 24, v48
	v_ashrrev_i32_e32 v45, 31, v44
	v_lshlrev_b64 v[48:49], 11, v[44:45]
	v_lshl_add_u64 v[44:45], v[50:51], 0, v[48:49]
	v_lshl_add_u64 v[44:45], v[44:45], 0, s[30:31]
	global_load_dwordx4 v[44:47], v[44:45], off
	v_rcp_f32_e32 v50, v54
	v_lshrrev_b32_e32 v54, 1, v60
	v_mul_u32_u24_e32 v51, 0x110, v61
	v_and_b32_e32 v54, 16, v54
	v_add3_u32 v51, v55, v51, v54
	v_pk_mul_f32 v[16:17], v[16:17], v[50:51] op_sel_hi:[1,0]
	v_pk_mul_f32 v[18:19], v[18:19], v[50:51] op_sel_hi:[1,0]
	v_pk_mul_f32 v[0:1], v[0:1], v[50:51] op_sel_hi:[1,0]
	v_pk_mul_f32 v[2:3], v[2:3], v[50:51] op_sel_hi:[1,0]
	ds_write_b128 v51, v[16:19]
	v_pk_mul_f32 v[16:17], v[20:21], v[50:51] op_sel_hi:[1,0]
	v_pk_mul_f32 v[18:19], v[22:23], v[50:51] op_sel_hi:[1,0]
	ds_write_b128 v51, v[0:3] offset:128
	v_pk_mul_f32 v[0:1], v[4:5], v[50:51] op_sel_hi:[1,0]
	v_pk_mul_f32 v[2:3], v[6:7], v[50:51] op_sel_hi:[1,0]
	ds_write_b128 v51, v[16:19] offset:32
	v_pk_mul_f32 v[16:17], v[24:25], v[50:51] op_sel_hi:[1,0]
	v_pk_mul_f32 v[18:19], v[26:27], v[50:51] op_sel_hi:[1,0]
	ds_write_b128 v51, v[0:3] offset:160
	v_pk_mul_f32 v[0:1], v[8:9], v[50:51] op_sel_hi:[1,0]
	v_pk_mul_f32 v[2:3], v[10:11], v[50:51] op_sel_hi:[1,0]
	ds_write_b128 v51, v[16:19] offset:64
	v_pk_mul_f32 v[16:17], v[28:29], v[50:51] op_sel_hi:[1,0]
	v_pk_mul_f32 v[18:19], v[30:31], v[50:51] op_sel_hi:[1,0]
	ds_write_b128 v51, v[0:3] offset:192
	v_pk_mul_f32 v[0:1], v[12:13], v[50:51] op_sel_hi:[1,0]
	v_pk_mul_f32 v[2:3], v[14:15], v[50:51] op_sel_hi:[1,0]
	ds_write_b128 v51, v[16:19] offset:96
	ds_write_b128 v51, v[0:3] offset:224
	v_lshl_or_b32 v0, v63, 2, v55
	s_waitcnt lgkmcnt(0)
	v_mad_u32_u24 v12, v62, s36, v0
	ds_read_b128 v[0:3], v12
	ds_read_b128 v[4:7], v12 offset:16
	v_lshl_add_u64 v[8:9], s[8:9], 0, v[128:129]
	s_waitcnt vmcnt(3)
	v_lshlrev_b32_e32 v10, 16, v32
	v_and_b32_e32 v11, 0xffff0000, v32
	s_waitcnt lgkmcnt(1)
	v_pk_mul_f32 v[0:1], v[0:1], v[10:11]
	v_lshlrev_b32_e32 v10, 16, v33
	v_and_b32_e32 v11, 0xffff0000, v33
	v_pk_mul_f32 v[2:3], v[2:3], v[10:11]
	v_cvt_pk_bf16_f32 v0, v0, v1
	v_cvt_pk_bf16_f32 v1, v2, v3
	v_lshlrev_b32_e32 v2, 16, v34
	v_and_b32_e32 v3, 0xffff0000, v34
	s_waitcnt lgkmcnt(0)
	v_pk_mul_f32 v[2:3], v[4:5], v[2:3]
	v_lshlrev_b32_e32 v4, 16, v35
	v_and_b32_e32 v5, 0xffff0000, v35
	v_pk_mul_f32 v[4:5], v[6:7], v[4:5]
	v_cvt_pk_bf16_f32 v2, v2, v3
	v_cvt_pk_bf16_f32 v3, v4, v5
	v_lshl_add_u64 v[4:5], v[8:9], 0, v[56:57]
	v_lshl_add_u64 v[10:11], v[4:5], 0, s[30:31]
	ds_read_b128 v[4:7], v12 offset:2176
	global_store_dwordx4 v[10:11], v[0:3], off nt
	ds_read_b128 v[0:3], v12 offset:2192
	s_waitcnt vmcnt(3)
	v_lshlrev_b32_e32 v10, 16, v40
	v_and_b32_e32 v11, 0xffff0000, v40
	s_waitcnt lgkmcnt(1)
	v_pk_mul_f32 v[4:5], v[4:5], v[10:11]
	v_lshlrev_b32_e32 v10, 16, v41
	v_and_b32_e32 v11, 0xffff0000, v41
	v_pk_mul_f32 v[6:7], v[6:7], v[10:11]
	v_cvt_pk_bf16_f32 v4, v4, v5
	v_cvt_pk_bf16_f32 v5, v6, v7
	v_lshlrev_b32_e32 v6, 16, v42
	v_and_b32_e32 v7, 0xffff0000, v42
	s_waitcnt lgkmcnt(0)
	v_pk_mul_f32 v[0:1], v[0:1], v[6:7]
	s_nop 0
	v_cvt_pk_bf16_f32 v6, v0, v1
	v_lshlrev_b32_e32 v0, 16, v43
	v_and_b32_e32 v1, 0xffff0000, v43
	v_pk_mul_f32 v[0:1], v[2:3], v[0:1]
	s_nop 0
	v_cvt_pk_bf16_f32 v7, v0, v1
	v_lshl_add_u64 v[0:1], v[8:9], 0, v[58:59]
	v_lshl_add_u64 v[10:11], v[0:1], 0, s[30:31]
	ds_read_b128 v[0:3], v12 offset:4352
	global_store_dwordx4 v[10:11], v[4:7], off nt
	ds_read_b128 v[4:7], v12 offset:4368
	s_waitcnt vmcnt(3)
	v_lshlrev_b32_e32 v10, 16, v36
	v_and_b32_e32 v11, 0xffff0000, v36
	s_waitcnt lgkmcnt(1)
	v_pk_mul_f32 v[0:1], v[0:1], v[10:11]
	v_lshlrev_b32_e32 v10, 16, v37
	v_and_b32_e32 v11, 0xffff0000, v37
	v_pk_mul_f32 v[2:3], v[2:3], v[10:11]
	v_cvt_pk_bf16_f32 v0, v0, v1
	v_cvt_pk_bf16_f32 v1, v2, v3
	v_lshlrev_b32_e32 v2, 16, v38
	v_and_b32_e32 v3, 0xffff0000, v38
	s_waitcnt lgkmcnt(0)
	v_pk_mul_f32 v[2:3], v[4:5], v[2:3]
	v_lshlrev_b32_e32 v4, 16, v39
	v_and_b32_e32 v5, 0xffff0000, v39
	v_pk_mul_f32 v[4:5], v[6:7], v[4:5]
	v_cvt_pk_bf16_f32 v2, v2, v3
	v_cvt_pk_bf16_f32 v3, v4, v5
	v_lshl_add_u64 v[4:5], v[8:9], 0, v[52:53]
	v_lshl_add_u64 v[10:11], v[4:5], 0, s[30:31]
	ds_read_b128 v[4:7], v12 offset:6528
	global_store_dwordx4 v[10:11], v[0:3], off nt
	ds_read_b128 v[0:3], v12 offset:6544
	s_waitcnt vmcnt(3)
	v_lshlrev_b32_e32 v10, 16, v44
	v_and_b32_e32 v11, 0xffff0000, v44
	s_waitcnt lgkmcnt(1)
	v_pk_mul_f32 v[4:5], v[4:5], v[10:11]
	v_lshlrev_b32_e32 v10, 16, v45
	v_and_b32_e32 v11, 0xffff0000, v45
	v_pk_mul_f32 v[6:7], v[6:7], v[10:11]
	v_cvt_pk_bf16_f32 v4, v4, v5
	v_cvt_pk_bf16_f32 v5, v6, v7
	v_lshlrev_b32_e32 v6, 16, v46
	v_and_b32_e32 v7, 0xffff0000, v46
	s_waitcnt lgkmcnt(0)
	v_pk_mul_f32 v[0:1], v[0:1], v[6:7]
	s_nop 0
	v_cvt_pk_bf16_f32 v6, v0, v1
	v_lshlrev_b32_e32 v0, 16, v47
	v_and_b32_e32 v1, 0xffff0000, v47
	v_pk_mul_f32 v[0:1], v[2:3], v[0:1]
	s_nop 0
	v_cvt_pk_bf16_f32 v7, v0, v1
	v_lshl_add_u64 v[0:1], v[8:9], 0, v[48:49]
	v_lshl_add_u64 v[0:1], v[0:1], 0, s[30:31]
	global_store_dwordx4 v[0:1], v[4:7], off nt
	s_barrier
	s_cbranch_scc0 .LBB0_175
